# epilogue vmcnt waits moved to first consumers (EpiIn rope variant, EpiRes residual prefetch)
# baseline (speedup 1.0000x reference)
.LBB0_580:
	s_lshl_b32 s0, s3, 11
	v_mbcnt_lo_u32_b32 v211, -1, 0
	v_mbcnt_hi_u32_b32 v211, -1, v211
	s_add_i32 s0, s61, s0
	v_and_b32_e32 v243, 15, v211
	v_ashrrev_i32_e32 v70, 4, v211
	s_movk_i32 s75, 0x2010
	v_lshl_add_u32 v74, v70, 5, s0
	v_lshlrev_b32_e32 v244, 3, v70
	ds_read_b128 v[102:105], v74
	ds_read_b128 v[90:93], v74 offset:16
	ds_read_b128 v[106:109], v74 offset:1024
	ds_read_b128 v[94:97], v74 offset:1040
	ds_read_b128 v[82:85], v74 offset:512
	ds_read_b128 v[70:73], v74 offset:528
	ds_read_b128 v[86:89], v74 offset:1536
	ds_read_b128 v[74:77], v74 offset:1552
	s_lshl_b32 s0, s42, 8
	s_add_i32 s3, s0, s7
	s_cmp_lg_u32 s40, 0
	s_cselect_b64 s[0:1], -1, 0
	s_cmp_lt_i32 s40, 7
	s_cselect_b64 s[42:43], -1, 0
	s_and_b64 s[44:45], s[0:1], s[42:43]
	v_add_u32_e32 v212, s3, v243
	s_mov_b64 s[42:43], -1
	s_and_b64 vcc, exec, s[44:45]
	v_add_u32_e32 v220, 16, v212
	v_add_u32_e32 v218, 32, v212
	v_add_u32_e32 v216, 48, v212
	v_add_u32_e32 v214, 0x80, v212
	s_movk_i32 s78, 0x3e0
	s_movk_i32 s79, 0x210
	s_movk_i32 s80, 0x2c00
	s_cbranch_vccz .LBB0_586
	s_cmp_gt_i32 s40, 2
	v_ashrrev_i32_e32 v213, 31, v212
	v_ashrrev_i32_e32 v221, 31, v220
	v_ashrrev_i32_e32 v219, 31, v218
	v_ashrrev_i32_e32 v217, 31, v216
	v_ashrrev_i32_e32 v215, 31, v214
	s_cbranch_scc0 .LBB0_583
	v_readlane_b32 s3, v255, 16
	v_lshlrev_b32_e32 v162, 6, v212
	v_and_b32_e32 v162, 0x7ffc0, v162
	v_add_u32_e32 v224, s3, v244
	v_add_u32_e32 v162, 0x400, v162
	v_mov_b32_e32 v163, v0
	v_ashrrev_i32_e32 v225, 31, v224
	v_lshl_add_u64 v[162:163], v[162:163], 0, v[224:225]
	v_lshl_add_u64 v[162:163], v[162:163], 3, s[22:23]
	global_load_dwordx4 v[182:185], v[162:163], off
	global_load_dwordx4 v[232:235], v[162:163], off offset:16
	global_load_dwordx4 v[178:181], v[162:163], off offset:32
	global_load_dwordx4 v[170:173], v[162:163], off offset:48
	v_lshlrev_b32_e32 v162, 6, v220
	v_and_b32_e32 v162, 0x7ffc0, v162
	v_mov_b32_e32 v163, v0
	v_add_u32_e32 v162, 0x400, v162
	v_lshl_add_u64 v[162:163], v[162:163], 0, v[224:225]
	v_lshl_add_u64 v[248:249], v[162:163], 3, s[22:23]
	global_load_dwordx4 v[174:177], v[248:249], off
	global_load_dwordx4 v[166:169], v[248:249], off offset:16
	global_load_dwordx4 v[162:165], v[248:249], off offset:32
	v_lshlrev_b32_e32 v245, 2, v243
	ds_bpermute_b32 v228, v245, v210
	ds_bpermute_b32 v246, v245, v209
	s_cmp_gt_u32 s40, 4
	s_cselect_b64 vcc, -1, 0
	s_lshl_b32 s3, s40, 1
	s_waitcnt lgkmcnt(0)
	v_pk_fma_f32 v[226:227], v[102:103], v[228:229], v[158:159] op_sel_hi:[1,0,1] neg_lo:[1,0,0] neg_hi:[1,0,0]
	v_pk_fma_f32 v[230:231], v[82:83], v[228:229], v[150:151] op_sel_hi:[1,0,1] neg_lo:[1,0,0] neg_hi:[1,0,0]
	v_pk_fma_f32 v[250:251], v[226:227], v[246:247], v[106:107] op_sel_hi:[1,0,1]
	v_pk_fma_f32 v[226:227], v[230:231], v[246:247], v[86:87] op_sel_hi:[1,0,1]
	s_and_b64 s[42:43], vcc, exec
	s_mov_b32 s25, 0x7944000
	s_cselect_b32 s27, s25, 0x693c000
	s_and_b32 s3, s3, 2
	v_readlane_b32 s25, v255, 12
	v_pk_fma_f32 v[236:237], v[104:105], v[228:229], v[160:161] op_sel_hi:[1,0,1] neg_lo:[1,0,0] neg_hi:[1,0,0]
	s_or_b32 s25, s3, s25
	v_pk_fma_f32 v[240:241], v[236:237], v[246:247], v[108:109] op_sel_hi:[1,0,1]
	s_add_u32 s3, s90, s27
	v_pk_fma_f32 v[252:253], v[90:91], v[228:229], v[154:155] op_sel_hi:[1,0,1] neg_lo:[1,0,0] neg_hi:[1,0,0]
	s_addc_u32 s27, s91, 0
	v_pk_fma_f32 v[236:237], v[252:253], v[246:247], v[94:95] op_sel_hi:[1,0,1]
	s_lshl_b32 s25, s25, 8
	s_xor_b32 s25, s25, 0x200
	v_cndmask_b32_e32 v222, 1.0, v247, vcc
	s_add_u32 s42, s3, s25
	s_addc_u32 s43, s27, 0
	s_waitcnt vmcnt(6)
	v_mov_b32_e32 v230, v182
	v_mov_b32_e32 v231, v184
	v_mov_b32_e32 v184, v183
	v_pk_mul_f32 v[182:183], v[184:185], v[226:227]
	v_pk_mul_f32 v[226:227], v[230:231], v[226:227]
	v_pk_fma_f32 v[230:231], v[230:231], v[250:251], v[182:183] neg_lo:[0,0,1] neg_hi:[0,0,1]
	v_pk_fma_f32 v[226:227], v[184:185], v[250:251], v[226:227]
	v_pk_fma_f32 v[184:185], v[84:85], v[228:229], v[152:153] op_sel_hi:[1,0,1] neg_lo:[1,0,0] neg_hi:[1,0,0]
	s_waitcnt vmcnt(5)
	v_mov_b32_e32 v250, v232
	v_pk_fma_f32 v[184:185], v[184:185], v[246:247], v[88:89] op_sel_hi:[1,0,1]
	v_mov_b32_e32 v251, v234
	v_mov_b32_e32 v234, v233
	v_pk_mul_f32 v[182:183], v[250:251], v[184:185]
	v_pk_mul_f32 v[238:239], v[234:235], v[184:185]
	v_pk_fma_f32 v[234:235], v[234:235], v[240:241], v[182:183]
	v_pk_fma_f32 v[182:183], v[70:71], v[228:229], v[146:147] op_sel_hi:[1,0,1] neg_lo:[1,0,0] neg_hi:[1,0,0]
	v_pk_fma_f32 v[184:185], v[92:93], v[228:229], v[156:157] op_sel_hi:[1,0,1] neg_lo:[1,0,0] neg_hi:[1,0,0]
	v_pk_fma_f32 v[232:233], v[72:73], v[228:229], v[148:149] op_sel_hi:[1,0,1] neg_lo:[1,0,0] neg_hi:[1,0,0]
	v_pk_fma_f32 v[252:253], v[182:183], v[246:247], v[74:75] op_sel_hi:[1,0,1]
	v_pk_fma_f32 v[238:239], v[250:251], v[240:241], v[238:239] neg_lo:[0,0,1] neg_hi:[0,0,1]
	s_waitcnt vmcnt(4)
	v_mov_b32_e32 v240, v178
	v_mov_b32_e32 v241, v180
	v_mov_b32_e32 v180, v179
	v_pk_fma_f32 v[228:229], v[184:185], v[246:247], v[96:97] op_sel_hi:[1,0,1]
	v_pk_fma_f32 v[232:233], v[232:233], v[246:247], v[76:77] op_sel_hi:[1,0,1]
	global_load_dwordx4 v[182:185], v[248:249], off offset:48
	v_pk_mul_f32 v[248:249], v[180:181], v[252:253]
	v_pk_mul_f32 v[178:179], v[240:241], v[252:253]
	s_waitcnt vmcnt(4)
	v_mov_b32_e32 v251, v172
	v_mov_b32_e32 v172, v171
	v_pk_fma_f32 v[180:181], v[180:181], v[236:237], v[178:179]
	v_mov_b32_e32 v250, v170
	v_pk_fma_f32 v[170:171], v[240:241], v[236:237], v[248:249] neg_lo:[0,0,1] neg_hi:[0,0,1]
	v_pk_mul_f32 v[236:237], v[172:173], v[232:233]
	v_pk_mul_f32 v[240:241], v[222:223], v[170:171] op_sel_hi:[0,1]
	v_pk_fma_f32 v[236:237], v[250:251], v[228:229], v[236:237] neg_lo:[0,0,1] neg_hi:[0,0,1]
	v_pk_mul_f32 v[180:181], v[222:223], v[180:181] op_sel_hi:[0,1]
	v_pk_mul_f32 v[170:171], v[250:251], v[232:233]
	v_lshl_add_u64 v[178:179], v[224:225], 1, s[42:43]
	v_pk_mul_f32 v[230:231], v[222:223], v[230:231] op_sel_hi:[0,1]
	v_pk_mul_f32 v[238:239], v[222:223], v[238:239] op_sel_hi:[0,1]
	v_pk_mul_f32 v[236:237], v[222:223], v[236:237] op_sel_hi:[0,1]
	v_pk_fma_f32 v[170:171], v[172:173], v[228:229], v[170:171]
	v_cvt_pk_bf16_f32 v228, v180, v181
	v_lshlrev_b64 v[180:181], 10, v[212:213]
	v_pk_mul_f32 v[226:227], v[222:223], v[226:227] op_sel_hi:[0,1]
	v_pk_mul_f32 v[234:235], v[222:223], v[234:235] op_sel_hi:[0,1]
	v_pk_mul_f32 v[232:233], v[222:223], v[170:171] op_sel_hi:[0,1]
	v_cvt_pk_bf16_f32 v170, v230, v231
	v_cvt_pk_bf16_f32 v171, v238, v239
	v_cvt_pk_bf16_f32 v172, v240, v241
	v_cvt_pk_bf16_f32 v173, v236, v237
	v_lshl_add_u64 v[180:181], v[178:179], 0, v[180:181]
	v_cvt_pk_bf16_f32 v226, v226, v227
	v_cvt_pk_bf16_f32 v227, v234, v235
	v_cvt_pk_bf16_f32 v229, v232, v233
	global_store_dwordx4 v[180:181], v[170:173], off
	global_store_dwordx4 v[180:181], v[226:229], off offset:128
	ds_bpermute_b32 v180, v245, v210 offset:64
	ds_bpermute_b32 v234, v245, v209 offset:64
	v_lshlrev_b32_e32 v170, 6, v218
	v_and_b32_e32 v170, 0x7ffc0, v170
	v_add_u32_e32 v170, 0x400, v170
	v_mov_b32_e32 v171, v0
	v_lshl_add_u64 v[170:171], v[170:171], 0, v[224:225]
	s_waitcnt lgkmcnt(0)
	v_pk_fma_f32 v[240:241], v[82:83], v[180:181], v[134:135] op_sel_hi:[1,0,1] neg_lo:[1,0,0] neg_hi:[1,0,0]
	v_lshl_add_u64 v[236:237], v[170:171], 3, s[22:23]
	v_pk_fma_f32 v[238:239], v[102:103], v[180:181], v[142:143] op_sel_hi:[1,0,1] neg_lo:[1,0,0] neg_hi:[1,0,0]
	v_pk_fma_f32 v[240:241], v[240:241], v[234:235], v[86:87] op_sel_hi:[1,0,1]
	s_waitcnt vmcnt(5)
	v_mov_b32_e32 v248, v174
	v_mov_b32_e32 v249, v176
	v_mov_b32_e32 v176, v175
	global_load_dwordx4 v[170:173], v[236:237], off
	global_load_dwordx4 v[226:229], v[236:237], off offset:16
	global_load_dwordx4 v[230:233], v[236:237], off offset:32
	v_pk_fma_f32 v[238:239], v[238:239], v[234:235], v[106:107] op_sel_hi:[1,0,1]
	v_pk_mul_f32 v[174:175], v[176:177], v[240:241]
	v_pk_mul_f32 v[240:241], v[248:249], v[240:241]
	v_pk_fma_f32 v[174:175], v[248:249], v[238:239], v[174:175] neg_lo:[0,0,1] neg_hi:[0,0,1]
	v_pk_fma_f32 v[176:177], v[176:177], v[238:239], v[240:241]
	v_pk_fma_f32 v[240:241], v[84:85], v[180:181], v[136:137] op_sel_hi:[1,0,1] neg_lo:[1,0,0] neg_hi:[1,0,0]
	v_pk_fma_f32 v[238:239], v[104:105], v[180:181], v[144:145] op_sel_hi:[1,0,1] neg_lo:[1,0,0] neg_hi:[1,0,0]
	v_pk_fma_f32 v[240:241], v[240:241], v[234:235], v[88:89] op_sel_hi:[1,0,1]
	s_waitcnt vmcnt(7)
	v_mov_b32_e32 v249, v168
	v_mov_b32_e32 v168, v167
	v_pk_fma_f32 v[238:239], v[238:239], v[234:235], v[108:109] op_sel_hi:[1,0,1]
	v_mov_b32_e32 v248, v166
	v_pk_mul_f32 v[166:167], v[168:169], v[240:241]
	v_pk_mul_f32 v[174:175], v[222:223], v[174:175] op_sel_hi:[0,1]
	v_pk_fma_f32 v[250:251], v[248:249], v[238:239], v[166:167] neg_lo:[0,0,1] neg_hi:[0,0,1]
	v_pk_mul_f32 v[166:167], v[248:249], v[240:241]
	v_pk_mul_f32 v[176:177], v[222:223], v[176:177] op_sel_hi:[0,1]
	v_pk_fma_f32 v[238:239], v[168:169], v[238:239], v[166:167]
	v_pk_fma_f32 v[166:167], v[90:91], v[180:181], v[138:139] op_sel_hi:[1,0,1] neg_lo:[1,0,0] neg_hi:[1,0,0]
	s_waitcnt vmcnt(6)
	v_mov_b32_e32 v169, v164
	v_pk_fma_f32 v[240:241], v[166:167], v[234:235], v[94:95] op_sel_hi:[1,0,1]
	v_pk_fma_f32 v[166:167], v[70:71], v[180:181], v[130:131] op_sel_hi:[1,0,1] neg_lo:[1,0,0] neg_hi:[1,0,0]
	v_mov_b32_e32 v164, v163
	v_pk_fma_f32 v[166:167], v[166:167], v[234:235], v[74:75] op_sel_hi:[1,0,1]
	v_mov_b32_e32 v168, v162
	v_pk_mul_f32 v[162:163], v[164:165], v[166:167]
	v_pk_mul_f32 v[248:249], v[168:169], v[166:167]
	v_pk_fma_f32 v[162:163], v[168:169], v[240:241], v[162:163] neg_lo:[0,0,1] neg_hi:[0,0,1]
	global_load_dwordx4 v[166:169], v[236:237], off offset:48
	v_pk_mul_f32 v[236:237], v[222:223], v[250:251] op_sel_hi:[0,1]
	v_pk_mul_f32 v[250:251], v[222:223], v[162:163] op_sel_hi:[0,1]
	v_pk_fma_f32 v[162:163], v[164:165], v[240:241], v[248:249]
	v_pk_fma_f32 v[164:165], v[72:73], v[180:181], v[132:133] op_sel_hi:[1,0,1] neg_lo:[1,0,0] neg_hi:[1,0,0]
	v_pk_mul_f32 v[240:241], v[222:223], v[162:163] op_sel_hi:[0,1]
	v_pk_fma_f32 v[162:163], v[92:93], v[180:181], v[140:141] op_sel_hi:[1,0,1] neg_lo:[1,0,0] neg_hi:[1,0,0]
	v_pk_fma_f32 v[164:165], v[164:165], v[234:235], v[76:77] op_sel_hi:[1,0,1]
	s_waitcnt vmcnt(6)
	v_mov_b32_e32 v180, v182
	v_mov_b32_e32 v181, v184
	v_mov_b32_e32 v184, v183
	v_pk_fma_f32 v[162:163], v[162:163], v[234:235], v[96:97] op_sel_hi:[1,0,1]
	v_pk_mul_f32 v[182:183], v[184:185], v[164:165]
	v_pk_mul_f32 v[164:165], v[180:181], v[164:165]
	v_pk_fma_f32 v[182:183], v[180:181], v[162:163], v[182:183] neg_lo:[0,0,1] neg_hi:[0,0,1]
	v_pk_fma_f32 v[162:163], v[184:185], v[162:163], v[164:165]
	ds_bpermute_b32 v184, v245, v210 offset:128
	v_pk_mul_f32 v[180:181], v[222:223], v[162:163] op_sel_hi:[0,1]
	v_pk_mul_f32 v[182:183], v[222:223], v[182:183] op_sel_hi:[0,1]
	v_cvt_pk_bf16_f32 v162, v174, v175
	v_cvt_pk_bf16_f32 v174, v176, v177
	v_cvt_pk_bf16_f32 v177, v180, v181
	v_lshlrev_b64 v[180:181], 10, v[220:221]
	ds_bpermute_b32 v234, v245, v209 offset:128
	v_pk_mul_f32 v[238:239], v[222:223], v[238:239] op_sel_hi:[0,1]
	v_cvt_pk_bf16_f32 v163, v236, v237
	v_cvt_pk_bf16_f32 v164, v250, v251
	v_cvt_pk_bf16_f32 v165, v182, v183
	v_lshl_add_u64 v[180:181], v[178:179], 0, v[180:181]
	v_cvt_pk_bf16_f32 v175, v238, v239
	v_cvt_pk_bf16_f32 v176, v240, v241
	global_store_dwordx4 v[180:181], v[162:165], off
	global_store_dwordx4 v[180:181], v[174:177], off offset:128
	s_waitcnt lgkmcnt(0)
	v_pk_fma_f32 v[240:241], v[82:83], v[184:185], v[118:119] op_sel_hi:[1,0,1] neg_lo:[1,0,0] neg_hi:[1,0,0]
	v_lshlrev_b32_e32 v162, 6, v216
	v_and_b32_e32 v162, 0x7ffc0, v162
	v_add_u32_e32 v162, 0x400, v162
	v_mov_b32_e32 v163, v0
	v_lshl_add_u64 v[162:163], v[162:163], 0, v[224:225]
	v_pk_fma_f32 v[238:239], v[102:103], v[184:185], v[126:127] op_sel_hi:[1,0,1] neg_lo:[1,0,0] neg_hi:[1,0,0]
	v_pk_fma_f32 v[240:241], v[240:241], v[234:235], v[86:87] op_sel_hi:[1,0,1]
	v_lshl_add_u64 v[236:237], v[162:163], 3, s[22:23]
	v_pk_fma_f32 v[238:239], v[238:239], v[234:235], v[106:107] op_sel_hi:[1,0,1]
	global_load_dwordx4 v[162:165], v[236:237], off
	global_load_dwordx4 v[174:177], v[236:237], off offset:16
	global_load_dwordx4 v[180:183], v[236:237], off offset:32
	s_mov_b64 s[42:43], 0
	s_waitcnt vmcnt(8)
	v_mov_b32_e32 v249, v172
	v_mov_b32_e32 v172, v171
	v_mov_b32_e32 v248, v170
	v_pk_mul_f32 v[170:171], v[172:173], v[240:241]
	s_nop 0
	v_pk_fma_f32 v[250:251], v[248:249], v[238:239], v[170:171] neg_lo:[0,0,1] neg_hi:[0,0,1]
	v_pk_mul_f32 v[170:171], v[248:249], v[240:241]
	s_waitcnt vmcnt(7)
	v_mov_b32_e32 v240, v226
	v_pk_fma_f32 v[238:239], v[172:173], v[238:239], v[170:171]
	v_pk_fma_f32 v[172:173], v[84:85], v[184:185], v[120:121] op_sel_hi:[1,0,1] neg_lo:[1,0,0] neg_hi:[1,0,0]
	v_pk_fma_f32 v[170:171], v[104:105], v[184:185], v[128:129] op_sel_hi:[1,0,1] neg_lo:[1,0,0] neg_hi:[1,0,0]
	v_pk_fma_f32 v[172:173], v[172:173], v[234:235], v[88:89] op_sel_hi:[1,0,1]
	v_mov_b32_e32 v241, v228
	v_mov_b32_e32 v228, v227
	v_pk_fma_f32 v[170:171], v[170:171], v[234:235], v[108:109] op_sel_hi:[1,0,1]
	v_pk_mul_f32 v[226:227], v[228:229], v[172:173]
	v_pk_mul_f32 v[172:173], v[240:241], v[172:173]
	v_pk_fma_f32 v[226:227], v[240:241], v[170:171], v[226:227] neg_lo:[0,0,1] neg_hi:[0,0,1]
	v_pk_fma_f32 v[228:229], v[228:229], v[170:171], v[172:173]
	v_pk_fma_f32 v[170:171], v[90:91], v[184:185], v[122:123] op_sel_hi:[1,0,1] neg_lo:[1,0,0] neg_hi:[1,0,0]
	s_waitcnt vmcnt(6)
	v_mov_b32_e32 v172, v230
	v_pk_fma_f32 v[240:241], v[170:171], v[234:235], v[94:95] op_sel_hi:[1,0,1]
	v_pk_fma_f32 v[170:171], v[70:71], v[184:185], v[114:115] op_sel_hi:[1,0,1] neg_lo:[1,0,0] neg_hi:[1,0,0]
	v_mov_b32_e32 v173, v232
	v_pk_fma_f32 v[170:171], v[170:171], v[234:235], v[74:75] op_sel_hi:[1,0,1]
	v_mov_b32_e32 v232, v231
	v_pk_mul_f32 v[230:231], v[232:233], v[170:171]
	v_pk_mul_f32 v[248:249], v[172:173], v[170:171]
	v_pk_fma_f32 v[230:231], v[172:173], v[240:241], v[230:231] neg_lo:[0,0,1] neg_hi:[0,0,1]
	v_pk_fma_f32 v[232:233], v[232:233], v[240:241], v[248:249]
	v_pk_fma_f32 v[240:241], v[92:93], v[184:185], v[124:125] op_sel_hi:[1,0,1] neg_lo:[1,0,0] neg_hi:[1,0,0]
	v_pk_fma_f32 v[184:185], v[72:73], v[184:185], v[116:117] op_sel_hi:[1,0,1] neg_lo:[1,0,0] neg_hi:[1,0,0]
	global_load_dwordx4 v[170:173], v[236:237], off offset:48
	v_pk_fma_f32 v[240:241], v[240:241], v[234:235], v[96:97] op_sel_hi:[1,0,1]
	v_pk_fma_f32 v[184:185], v[184:185], v[234:235], v[76:77] op_sel_hi:[1,0,1]
	s_waitcnt vmcnt(6)
	v_mov_b32_e32 v235, v168
	v_mov_b32_e32 v168, v167
	v_mov_b32_e32 v234, v166
	v_pk_mul_f32 v[166:167], v[168:169], v[184:185]
	v_pk_mul_f32 v[226:227], v[222:223], v[226:227] op_sel_hi:[0,1]
	v_pk_fma_f32 v[166:167], v[234:235], v[240:241], v[166:167] neg_lo:[0,0,1] neg_hi:[0,0,1]
	v_pk_mul_f32 v[228:229], v[222:223], v[228:229] op_sel_hi:[0,1]
	v_pk_mul_f32 v[248:249], v[222:223], v[166:167] op_sel_hi:[0,1]
	v_pk_mul_f32 v[166:167], v[234:235], v[184:185]
	v_pk_mul_f32 v[236:237], v[222:223], v[250:251] op_sel_hi:[0,1]
	v_pk_fma_f32 v[166:167], v[168:169], v[240:241], v[166:167]
	v_pk_mul_f32 v[230:231], v[222:223], v[230:231] op_sel_hi:[0,1]
	v_pk_mul_f32 v[184:185], v[222:223], v[166:167] op_sel_hi:[0,1]
	v_cvt_pk_bf16_f32 v167, v226, v227
	v_cvt_pk_bf16_f32 v227, v228, v229
	v_cvt_pk_bf16_f32 v229, v184, v185
	v_lshlrev_b64 v[184:185], 10, v[218:219]
	v_pk_mul_f32 v[238:239], v[222:223], v[238:239] op_sel_hi:[0,1]
	v_pk_mul_f32 v[232:233], v[222:223], v[232:233] op_sel_hi:[0,1]
	v_cvt_pk_bf16_f32 v166, v236, v237
	v_cvt_pk_bf16_f32 v168, v230, v231
	v_cvt_pk_bf16_f32 v169, v248, v249
	v_lshl_add_u64 v[184:185], v[178:179], 0, v[184:185]
	v_cvt_pk_bf16_f32 v226, v238, v239
	v_cvt_pk_bf16_f32 v228, v232, v233
	global_store_dwordx4 v[184:185], v[166:169], off
	global_store_dwordx4 v[184:185], v[226:229], off offset:128
	ds_bpermute_b32 v184, v245, v210 offset:192
	v_lshlrev_b32_e32 v166, 6, v214
	v_and_b32_e32 v166, 0x7ffc0, v166
	v_add_u32_e32 v166, 0x400, v166
	v_mov_b32_e32 v167, v0
	v_lshl_add_u64 v[166:167], v[166:167], 0, v[224:225]
	v_lshl_add_u64 v[236:237], v[166:167], 3, s[22:23]
	global_load_dwordx4 v[166:169], v[236:237], off
	global_load_dwordx4 v[226:229], v[236:237], off offset:16
	global_load_dwordx4 v[230:233], v[236:237], off offset:32
	ds_bpermute_b32 v234, v245, v209 offset:192
	s_waitcnt lgkmcnt(0)
	v_pk_fma_f32 v[240:241], v[82:83], v[184:185], v[78:79] op_sel_hi:[1,0,1] neg_lo:[1,0,0] neg_hi:[1,0,0]
	v_pk_fma_f32 v[238:239], v[102:103], v[184:185], v[110:111] op_sel_hi:[1,0,1] neg_lo:[1,0,0] neg_hi:[1,0,0]
	s_waitcnt vmcnt(8)
	v_mov_b32_e32 v248, v162
	v_mov_b32_e32 v249, v164
	v_pk_fma_f32 v[240:241], v[240:241], v[234:235], v[86:87] op_sel_hi:[1,0,1]
	v_mov_b32_e32 v164, v163
	v_pk_fma_f32 v[238:239], v[238:239], v[234:235], v[106:107] op_sel_hi:[1,0,1]
	v_pk_mul_f32 v[162:163], v[164:165], v[240:241]
	v_pk_mul_f32 v[240:241], v[248:249], v[240:241]
	v_pk_fma_f32 v[162:163], v[248:249], v[238:239], v[162:163] neg_lo:[0,0,1] neg_hi:[0,0,1]
	v_pk_fma_f32 v[164:165], v[164:165], v[238:239], v[240:241]
	v_pk_fma_f32 v[240:241], v[84:85], v[184:185], v[80:81] op_sel_hi:[1,0,1] neg_lo:[1,0,0] neg_hi:[1,0,0]
	v_pk_fma_f32 v[238:239], v[104:105], v[184:185], v[112:113] op_sel_hi:[1,0,1] neg_lo:[1,0,0] neg_hi:[1,0,0]
	v_pk_fma_f32 v[240:241], v[240:241], v[234:235], v[88:89] op_sel_hi:[1,0,1]
	s_waitcnt vmcnt(7)
	v_mov_b32_e32 v249, v176
	v_mov_b32_e32 v176, v175
	v_pk_fma_f32 v[238:239], v[238:239], v[234:235], v[108:109] op_sel_hi:[1,0,1]
	v_mov_b32_e32 v248, v174
	v_pk_mul_f32 v[174:175], v[176:177], v[240:241]
	v_pk_mul_f32 v[162:163], v[222:223], v[162:163] op_sel_hi:[0,1]
	v_pk_fma_f32 v[250:251], v[248:249], v[238:239], v[174:175] neg_lo:[0,0,1] neg_hi:[0,0,1]
	v_pk_mul_f32 v[174:175], v[248:249], v[240:241]
	v_cvt_pk_bf16_f32 v162, v162, v163
	v_pk_fma_f32 v[238:239], v[176:177], v[238:239], v[174:175]
	v_pk_fma_f32 v[174:175], v[90:91], v[184:185], v[98:99] op_sel_hi:[1,0,1] neg_lo:[1,0,0] neg_hi:[1,0,0]
	s_waitcnt vmcnt(6)
	v_mov_b32_e32 v176, v180
	v_pk_fma_f32 v[240:241], v[174:175], v[234:235], v[94:95] op_sel_hi:[1,0,1]
	v_pk_fma_f32 v[174:175], v[70:71], v[184:185], v[66:67] op_sel_hi:[1,0,1] neg_lo:[1,0,0] neg_hi:[1,0,0]
	v_mov_b32_e32 v177, v182
	v_pk_fma_f32 v[174:175], v[174:175], v[234:235], v[74:75] op_sel_hi:[1,0,1]
	v_mov_b32_e32 v182, v181
	v_pk_mul_f32 v[180:181], v[182:183], v[174:175]
	v_pk_mul_f32 v[248:249], v[176:177], v[174:175]
	v_pk_fma_f32 v[180:181], v[176:177], v[240:241], v[180:181] neg_lo:[0,0,1] neg_hi:[0,0,1]
	v_pk_fma_f32 v[182:183], v[182:183], v[240:241], v[248:249]
	v_pk_fma_f32 v[240:241], v[92:93], v[184:185], v[100:101] op_sel_hi:[1,0,1] neg_lo:[1,0,0] neg_hi:[1,0,0]
	v_pk_fma_f32 v[184:185], v[72:73], v[184:185], v[68:69] op_sel_hi:[1,0,1] neg_lo:[1,0,0] neg_hi:[1,0,0]
	v_pk_fma_f32 v[240:241], v[240:241], v[234:235], v[96:97] op_sel_hi:[1,0,1]
	v_pk_fma_f32 v[184:185], v[184:185], v[234:235], v[76:77] op_sel_hi:[1,0,1]
	global_load_dwordx4 v[174:177], v[236:237], off offset:48
	v_pk_mul_f32 v[236:237], v[222:223], v[164:165] op_sel_hi:[0,1]
	v_pk_mul_f32 v[164:165], v[222:223], v[250:251] op_sel_hi:[0,1]
	s_waitcnt vmcnt(6)
	v_mov_b32_e32 v235, v172
	v_mov_b32_e32 v172, v171
	v_mov_b32_e32 v234, v170
	v_pk_mul_f32 v[170:171], v[172:173], v[184:185]
	v_pk_mul_f32 v[180:181], v[222:223], v[180:181] op_sel_hi:[0,1]
	v_pk_fma_f32 v[170:171], v[234:235], v[240:241], v[170:171] neg_lo:[0,0,1] neg_hi:[0,0,1]
	v_pk_mul_f32 v[184:185], v[234:235], v[184:185]
	v_pk_mul_f32 v[170:171], v[222:223], v[170:171] op_sel_hi:[0,1]
	v_pk_fma_f32 v[172:173], v[172:173], v[240:241], v[184:185]
	v_cvt_pk_bf16_f32 v163, v164, v165
	v_cvt_pk_bf16_f32 v164, v180, v181
	v_lshlrev_b64 v[180:181], 10, v[216:217]
	v_pk_mul_f32 v[238:239], v[222:223], v[238:239] op_sel_hi:[0,1]
	v_pk_mul_f32 v[182:183], v[222:223], v[182:183] op_sel_hi:[0,1]
	v_pk_mul_f32 v[184:185], v[222:223], v[172:173] op_sel_hi:[0,1]
	v_cvt_pk_bf16_f32 v165, v170, v171
	v_lshl_add_u64 v[180:181], v[178:179], 0, v[180:181]
	v_cvt_pk_bf16_f32 v170, v236, v237
	v_cvt_pk_bf16_f32 v171, v238, v239
	v_cvt_pk_bf16_f32 v172, v182, v183
	v_cvt_pk_bf16_f32 v173, v184, v185
	global_store_dwordx4 v[180:181], v[162:165], off
	global_store_dwordx4 v[180:181], v[170:173], off offset:128
	ds_bpermute_b32 v162, v245, v208
	ds_bpermute_b32 v184, v245, v189
	v_add_u32_e32 v164, 0x90, v212
	v_lshlrev_b32_e32 v163, 6, v164
	v_and_b32_e32 v163, 0x7ffc0, v163
	s_waitcnt lgkmcnt(0)
	v_pk_fma_f32 v[238:239], v[82:83], v[162:163], v[54:55] op_sel_hi:[1,0,1] neg_lo:[1,0,0] neg_hi:[1,0,0]
	v_add_u32_e32 v170, 0x400, v163
	v_mov_b32_e32 v171, v0
	v_pk_fma_f32 v[236:237], v[102:103], v[162:163], v[62:63] op_sel_hi:[1,0,1] neg_lo:[1,0,0] neg_hi:[1,0,0]
	v_pk_fma_f32 v[238:239], v[238:239], v[184:185], v[86:87] op_sel_hi:[1,0,1]
	v_lshl_add_u64 v[170:171], v[170:171], 0, v[224:225]
	v_pk_fma_f32 v[236:237], v[236:237], v[184:185], v[106:107] op_sel_hi:[1,0,1]
	s_waitcnt vmcnt(5)
	v_mov_b32_e32 v241, v168
	v_mov_b32_e32 v168, v167
	v_mov_b32_e32 v240, v166
	v_pk_mul_f32 v[166:167], v[168:169], v[238:239]
	v_lshl_add_u64 v[234:235], v[170:171], 3, s[22:23]
	v_pk_fma_f32 v[248:249], v[240:241], v[236:237], v[166:167] neg_lo:[0,0,1] neg_hi:[0,0,1]
	v_pk_mul_f32 v[166:167], v[240:241], v[238:239]
	global_load_dwordx4 v[170:173], v[234:235], off
	global_load_dwordx4 v[180:183], v[234:235], off offset:16
	v_pk_fma_f32 v[236:237], v[168:169], v[236:237], v[166:167]
	v_pk_fma_f32 v[168:169], v[84:85], v[162:163], v[56:57] op_sel_hi:[1,0,1] neg_lo:[1,0,0] neg_hi:[1,0,0]
	v_pk_fma_f32 v[166:167], v[104:105], v[162:163], v[64:65] op_sel_hi:[1,0,1] neg_lo:[1,0,0] neg_hi:[1,0,0]
	v_pk_fma_f32 v[168:169], v[168:169], v[184:185], v[88:89] op_sel_hi:[1,0,1]
	s_waitcnt vmcnt(6)
	v_mov_b32_e32 v238, v226
	v_mov_b32_e32 v239, v228
	v_mov_b32_e32 v228, v227
	v_pk_fma_f32 v[166:167], v[166:167], v[184:185], v[108:109] op_sel_hi:[1,0,1]
	v_pk_mul_f32 v[226:227], v[228:229], v[168:169]
	v_pk_mul_f32 v[168:169], v[238:239], v[168:169]
	v_pk_fma_f32 v[240:241], v[238:239], v[166:167], v[226:227] neg_lo:[0,0,1] neg_hi:[0,0,1]
	v_pk_fma_f32 v[238:239], v[228:229], v[166:167], v[168:169]
	v_pk_fma_f32 v[166:167], v[90:91], v[162:163], v[58:59] op_sel_hi:[1,0,1] neg_lo:[1,0,0] neg_hi:[1,0,0]
	s_waitcnt vmcnt(5)
	v_mov_b32_e32 v252, v230
	v_pk_fma_f32 v[250:251], v[166:167], v[184:185], v[94:95] op_sel_hi:[1,0,1]
	v_pk_fma_f32 v[166:167], v[70:71], v[162:163], v[50:51] op_sel_hi:[1,0,1] neg_lo:[1,0,0] neg_hi:[1,0,0]
	v_mov_b32_e32 v253, v232
	v_pk_fma_f32 v[166:167], v[166:167], v[184:185], v[74:75] op_sel_hi:[1,0,1]
	v_mov_b32_e32 v232, v231
	v_pk_mul_f32 v[230:231], v[232:233], v[166:167]
	v_pk_mul_f32 v[166:167], v[252:253], v[166:167]
	v_pk_fma_f32 v[230:231], v[252:253], v[250:251], v[230:231] neg_lo:[0,0,1] neg_hi:[0,0,1]
	v_pk_fma_f32 v[232:233], v[232:233], v[250:251], v[166:167]
	global_load_dwordx4 v[166:169], v[234:235], off offset:32
	global_load_dwordx4 v[226:229], v[234:235], off offset:48
	v_pk_mul_f32 v[234:235], v[222:223], v[248:249] op_sel_hi:[0,1]
	v_pk_fma_f32 v[248:249], v[92:93], v[162:163], v[60:61] op_sel_hi:[1,0,1] neg_lo:[1,0,0] neg_hi:[1,0,0]
	v_pk_fma_f32 v[162:163], v[72:73], v[162:163], v[52:53] op_sel_hi:[1,0,1] neg_lo:[1,0,0] neg_hi:[1,0,0]
	v_pk_fma_f32 v[248:249], v[248:249], v[184:185], v[96:97] op_sel_hi:[1,0,1]
	v_pk_fma_f32 v[162:163], v[162:163], v[184:185], v[76:77] op_sel_hi:[1,0,1]
	v_pk_mul_f32 v[232:233], v[222:223], v[232:233] op_sel_hi:[0,1]
	v_pk_mul_f32 v[240:241], v[222:223], v[240:241] op_sel_hi:[0,1]
	v_pk_mul_f32 v[230:231], v[222:223], v[230:231] op_sel_hi:[0,1]
	v_cvt_pk_bf16_f32 v232, v232, v233
	v_pk_mul_f32 v[236:237], v[222:223], v[236:237] op_sel_hi:[0,1]
	v_pk_mul_f32 v[238:239], v[222:223], v[238:239] op_sel_hi:[0,1]
	s_waitcnt vmcnt(6)
	v_mov_b32_e32 v184, v174
	v_mov_b32_e32 v185, v176
	v_mov_b32_e32 v176, v175
	v_pk_mul_f32 v[174:175], v[176:177], v[162:163]
	v_pk_mul_f32 v[162:163], v[184:185], v[162:163]
	v_pk_fma_f32 v[174:175], v[184:185], v[248:249], v[174:175] neg_lo:[0,0,1] neg_hi:[0,0,1]
	v_pk_fma_f32 v[162:163], v[176:177], v[248:249], v[162:163]
	v_pk_mul_f32 v[250:251], v[222:223], v[174:175] op_sel_hi:[0,1]
	v_pk_mul_f32 v[162:163], v[222:223], v[162:163] op_sel_hi:[0,1]
	v_cvt_pk_bf16_f32 v233, v162, v163
	v_lshlrev_b64 v[162:163], 10, v[214:215]
	ds_bpermute_b32 v184, v245, v208 offset:64
	v_cvt_pk_bf16_f32 v174, v234, v235
	v_cvt_pk_bf16_f32 v175, v240, v241
	v_cvt_pk_bf16_f32 v176, v230, v231
	v_cvt_pk_bf16_f32 v177, v250, v251
	v_lshl_add_u64 v[162:163], v[178:179], 0, v[162:163]
	ds_bpermute_b32 v234, v245, v189 offset:64
	v_cvt_pk_bf16_f32 v230, v236, v237
	v_cvt_pk_bf16_f32 v231, v238, v239
	global_store_dwordx4 v[162:163], v[174:177], off
	global_store_dwordx4 v[162:163], v[230:233], off offset:128
	v_add_u32_e32 v162, 0xa0, v212
	v_lshlrev_b32_e32 v163, 6, v162
	v_and_b32_e32 v163, 0x7ffc0, v163
	v_add_u32_e32 v174, 0x400, v163
	v_mov_b32_e32 v175, v0
	s_waitcnt lgkmcnt(0)
	v_pk_fma_f32 v[240:241], v[82:83], v[184:185], v[38:39] op_sel_hi:[1,0,1] neg_lo:[1,0,0] neg_hi:[1,0,0]
	v_lshl_add_u64 v[174:175], v[174:175], 0, v[224:225]
	v_pk_fma_f32 v[238:239], v[102:103], v[184:185], v[46:47] op_sel_hi:[1,0,1] neg_lo:[1,0,0] neg_hi:[1,0,0]
	v_pk_fma_f32 v[240:241], v[240:241], v[234:235], v[86:87] op_sel_hi:[1,0,1]
	v_lshl_add_u64 v[236:237], v[174:175], 3, s[22:23]
	v_pk_fma_f32 v[238:239], v[238:239], v[234:235], v[106:107] op_sel_hi:[1,0,1]
	global_load_dwordx4 v[174:177], v[236:237], off
	global_load_dwordx4 v[230:233], v[236:237], off offset:16
	v_ashrrev_i32_e32 v165, 31, v164
	v_lshlrev_b64 v[164:165], 10, v[164:165]
	v_lshl_add_u64 v[164:165], v[178:179], 0, v[164:165]
	s_waitcnt vmcnt(7)
	v_mov_b32_e32 v249, v172
	v_mov_b32_e32 v172, v171
	v_mov_b32_e32 v248, v170
	v_pk_mul_f32 v[170:171], v[172:173], v[240:241]
	s_nop 0
	v_pk_fma_f32 v[250:251], v[248:249], v[238:239], v[170:171] neg_lo:[0,0,1] neg_hi:[0,0,1]
	v_pk_mul_f32 v[170:171], v[248:249], v[240:241]
	s_waitcnt vmcnt(6)
	v_mov_b32_e32 v240, v180
	v_pk_fma_f32 v[238:239], v[172:173], v[238:239], v[170:171]
	v_pk_fma_f32 v[172:173], v[84:85], v[184:185], v[40:41] op_sel_hi:[1,0,1] neg_lo:[1,0,0] neg_hi:[1,0,0]
	v_pk_fma_f32 v[170:171], v[104:105], v[184:185], v[48:49] op_sel_hi:[1,0,1] neg_lo:[1,0,0] neg_hi:[1,0,0]
	v_pk_fma_f32 v[172:173], v[172:173], v[234:235], v[88:89] op_sel_hi:[1,0,1]
	v_mov_b32_e32 v241, v182
	v_mov_b32_e32 v182, v181
	v_pk_fma_f32 v[170:171], v[170:171], v[234:235], v[108:109] op_sel_hi:[1,0,1]
	v_pk_mul_f32 v[180:181], v[182:183], v[172:173]
	v_pk_mul_f32 v[172:173], v[240:241], v[172:173]
	v_pk_fma_f32 v[180:181], v[240:241], v[170:171], v[180:181] neg_lo:[0,0,1] neg_hi:[0,0,1]
	v_pk_fma_f32 v[182:183], v[182:183], v[170:171], v[172:173]
	v_pk_fma_f32 v[172:173], v[70:71], v[184:185], v[34:35] op_sel_hi:[1,0,1] neg_lo:[1,0,0] neg_hi:[1,0,0]
	v_pk_fma_f32 v[170:171], v[90:91], v[184:185], v[42:43] op_sel_hi:[1,0,1] neg_lo:[1,0,0] neg_hi:[1,0,0]
	v_pk_fma_f32 v[172:173], v[172:173], v[234:235], v[74:75] op_sel_hi:[1,0,1]
	v_pk_fma_f32 v[170:171], v[170:171], v[234:235], v[94:95] op_sel_hi:[1,0,1]
	s_waitcnt vmcnt(5)
	v_mov_b32_e32 v240, v166
	v_mov_b32_e32 v241, v168
	v_mov_b32_e32 v168, v167
	v_pk_mul_f32 v[166:167], v[240:241], v[172:173]
	v_pk_mul_f32 v[248:249], v[168:169], v[172:173]
	v_pk_fma_f32 v[252:253], v[168:169], v[170:171], v[166:167]
	global_load_dwordx4 v[166:169], v[236:237], off offset:32
	v_pk_fma_f32 v[240:241], v[240:241], v[170:171], v[248:249] neg_lo:[0,0,1] neg_hi:[0,0,1]
	v_pk_fma_f32 v[170:171], v[92:93], v[184:185], v[44:45] op_sel_hi:[1,0,1] neg_lo:[1,0,0] neg_hi:[1,0,0]
	s_waitcnt vmcnt(5)
	v_mov_b32_e32 v173, v228
	v_pk_fma_f32 v[248:249], v[170:171], v[234:235], v[96:97] op_sel_hi:[1,0,1]
	v_pk_fma_f32 v[170:171], v[72:73], v[184:185], v[36:37] op_sel_hi:[1,0,1] neg_lo:[1,0,0] neg_hi:[1,0,0]
	v_mov_b32_e32 v228, v227
	v_pk_fma_f32 v[170:171], v[170:171], v[234:235], v[76:77] op_sel_hi:[1,0,1]
	v_mov_b32_e32 v172, v226
	v_pk_mul_f32 v[184:185], v[228:229], v[170:171]
	v_pk_mul_f32 v[226:227], v[172:173], v[170:171]
	v_pk_fma_f32 v[184:185], v[172:173], v[248:249], v[184:185] neg_lo:[0,0,1] neg_hi:[0,0,1]
	global_load_dwordx4 v[170:173], v[236:237], off offset:48
	v_pk_mul_f32 v[234:235], v[222:223], v[250:251] op_sel_hi:[0,1]
	v_pk_mul_f32 v[236:237], v[222:223], v[238:239] op_sel_hi:[0,1]
	v_pk_mul_f32 v[238:239], v[222:223], v[180:181] op_sel_hi:[0,1]
	v_pk_mul_f32 v[250:251], v[222:223], v[182:183] op_sel_hi:[0,1]
	v_pk_mul_f32 v[182:183], v[222:223], v[240:241] op_sel_hi:[0,1]
	v_pk_mul_f32 v[240:241], v[222:223], v[252:253] op_sel_hi:[0,1]
	v_pk_mul_f32 v[184:185], v[222:223], v[184:185] op_sel_hi:[0,1]
	v_pk_fma_f32 v[180:181], v[228:229], v[248:249], v[226:227]
	v_cvt_pk_bf16_f32 v182, v182, v183
	v_pk_mul_f32 v[248:249], v[222:223], v[180:181] op_sel_hi:[0,1]
	v_cvt_pk_bf16_f32 v180, v234, v235
	v_cvt_pk_bf16_f32 v181, v238, v239
	v_cvt_pk_bf16_f32 v183, v184, v185
	v_cvt_pk_bf16_f32 v228, v240, v241
	ds_bpermute_b32 v184, v245, v208 offset:128
	v_cvt_pk_bf16_f32 v226, v236, v237
	v_cvt_pk_bf16_f32 v227, v250, v251
	v_cvt_pk_bf16_f32 v229, v248, v249
	global_store_dwordx4 v[164:165], v[180:183], off
	global_store_dwordx4 v[164:165], v[226:229], off offset:128
	ds_bpermute_b32 v228, v245, v189 offset:128
	v_add_u32_e32 v164, 0xb0, v212
	v_lshlrev_b32_e32 v163, 6, v164
	s_waitcnt lgkmcnt(0)
	v_pk_fma_f32 v[238:239], v[82:83], v[184:185], v[22:23] op_sel_hi:[1,0,1] neg_lo:[1,0,0] neg_hi:[1,0,0]
	v_and_b32_e32 v163, 0x7ffc0, v163
	v_pk_fma_f32 v[236:237], v[102:103], v[184:185], v[30:31] op_sel_hi:[1,0,1] neg_lo:[1,0,0] neg_hi:[1,0,0]
	v_pk_fma_f32 v[238:239], v[238:239], v[228:229], v[86:87] op_sel_hi:[1,0,1]
	s_waitcnt vmcnt(5)
	v_mov_b32_e32 v241, v176
	v_mov_b32_e32 v176, v175
	v_add_u32_e32 v180, 0x400, v163
	v_mov_b32_e32 v181, v0
	v_pk_fma_f32 v[236:237], v[236:237], v[228:229], v[106:107] op_sel_hi:[1,0,1]
	v_mov_b32_e32 v240, v174
	v_pk_mul_f32 v[174:175], v[176:177], v[238:239]
	v_lshl_add_u64 v[180:181], v[180:181], 0, v[224:225]
	v_pk_fma_f32 v[248:249], v[240:241], v[236:237], v[174:175] neg_lo:[0,0,1] neg_hi:[0,0,1]
	v_pk_mul_f32 v[174:175], v[240:241], v[238:239]
	v_lshl_add_u64 v[234:235], v[180:181], 3, s[22:23]
	v_pk_fma_f32 v[236:237], v[176:177], v[236:237], v[174:175]
	v_pk_fma_f32 v[176:177], v[84:85], v[184:185], v[24:25] op_sel_hi:[1,0,1] neg_lo:[1,0,0] neg_hi:[1,0,0]
	global_load_dwordx4 v[180:183], v[234:235], off
	global_load_dwordx4 v[224:227], v[234:235], off offset:16
	v_pk_fma_f32 v[174:175], v[104:105], v[184:185], v[32:33] op_sel_hi:[1,0,1] neg_lo:[1,0,0] neg_hi:[1,0,0]
	v_pk_fma_f32 v[176:177], v[176:177], v[228:229], v[88:89] op_sel_hi:[1,0,1]
	s_waitcnt vmcnt(6)
	v_mov_b32_e32 v238, v230
	v_mov_b32_e32 v239, v232
	v_mov_b32_e32 v232, v231
	v_pk_fma_f32 v[174:175], v[174:175], v[228:229], v[108:109] op_sel_hi:[1,0,1]
	v_pk_mul_f32 v[230:231], v[232:233], v[176:177]
	v_pk_mul_f32 v[176:177], v[238:239], v[176:177]
	v_pk_fma_f32 v[230:231], v[238:239], v[174:175], v[230:231] neg_lo:[0,0,1] neg_hi:[0,0,1]
	v_pk_fma_f32 v[232:233], v[232:233], v[174:175], v[176:177]
	v_pk_fma_f32 v[174:175], v[90:91], v[184:185], v[26:27] op_sel_hi:[1,0,1] neg_lo:[1,0,0] neg_hi:[1,0,0]
	v_pk_mul_f32 v[230:231], v[222:223], v[230:231] op_sel_hi:[0,1]
	v_pk_fma_f32 v[238:239], v[174:175], v[228:229], v[94:95] op_sel_hi:[1,0,1]
	v_pk_fma_f32 v[174:175], v[70:71], v[184:185], v[18:19] op_sel_hi:[1,0,1] neg_lo:[1,0,0] neg_hi:[1,0,0]
	v_pk_mul_f32 v[232:233], v[222:223], v[232:233] op_sel_hi:[0,1]
	v_pk_fma_f32 v[174:175], v[174:175], v[228:229], v[74:75] op_sel_hi:[1,0,1]
	v_ashrrev_i32_e32 v163, 31, v162
	v_lshlrev_b64 v[162:163], 10, v[162:163]
	v_pk_mul_f32 v[236:237], v[222:223], v[236:237] op_sel_hi:[0,1]
	v_lshl_add_u64 v[162:163], v[178:179], 0, v[162:163]
	v_ashrrev_i32_e32 v165, 31, v164
	s_waitcnt vmcnt(5)
	v_mov_b32_e32 v240, v166
	v_mov_b32_e32 v241, v168
	v_mov_b32_e32 v168, v167
	v_pk_mul_f32 v[166:167], v[240:241], v[174:175]
	v_pk_mul_f32 v[250:251], v[168:169], v[174:175]
	v_pk_fma_f32 v[252:253], v[168:169], v[238:239], v[166:167]
	global_load_dwordx4 v[166:169], v[234:235], off offset:32
	global_load_dwordx4 v[174:177], v[234:235], off offset:48
	v_pk_mul_f32 v[234:235], v[222:223], v[248:249] op_sel_hi:[0,1]
	v_pk_fma_f32 v[248:249], v[92:93], v[184:185], v[28:29] op_sel_hi:[1,0,1] neg_lo:[1,0,0] neg_hi:[1,0,0]
	v_pk_fma_f32 v[184:185], v[72:73], v[184:185], v[20:21] op_sel_hi:[1,0,1] neg_lo:[1,0,0] neg_hi:[1,0,0]
	v_pk_fma_f32 v[248:249], v[248:249], v[228:229], v[96:97] op_sel_hi:[1,0,1]
	v_pk_fma_f32 v[184:185], v[184:185], v[228:229], v[76:77] op_sel_hi:[1,0,1]
	s_waitcnt vmcnt(6)
	v_mov_b32_e32 v229, v172
	v_mov_b32_e32 v172, v171
	v_mov_b32_e32 v228, v170
	v_pk_mul_f32 v[170:171], v[172:173], v[184:185]
	v_pk_fma_f32 v[238:239], v[240:241], v[238:239], v[250:251] neg_lo:[0,0,1] neg_hi:[0,0,1]
	v_pk_fma_f32 v[170:171], v[228:229], v[248:249], v[170:171] neg_lo:[0,0,1] neg_hi:[0,0,1]
	v_pk_mul_f32 v[238:239], v[222:223], v[238:239] op_sel_hi:[0,1]
	v_pk_mul_f32 v[250:251], v[222:223], v[170:171] op_sel_hi:[0,1]
	v_pk_mul_f32 v[170:171], v[228:229], v[184:185]
	v_cvt_pk_bf16_f32 v229, v232, v233
	v_pk_fma_f32 v[170:171], v[172:173], v[248:249], v[170:171]
	ds_bpermute_b32 v232, v245, v189 offset:192
	v_pk_mul_f32 v[184:185], v[222:223], v[170:171] op_sel_hi:[0,1]
	v_cvt_pk_bf16_f32 v171, v230, v231
	v_cvt_pk_bf16_f32 v231, v184, v185
	ds_bpermute_b32 v184, v245, v208 offset:192
	v_pk_mul_f32 v[240:241], v[222:223], v[252:253] op_sel_hi:[0,1]
	v_cvt_pk_bf16_f32 v170, v234, v235
	v_cvt_pk_bf16_f32 v172, v238, v239
	v_cvt_pk_bf16_f32 v173, v250, v251
	v_cvt_pk_bf16_f32 v228, v236, v237
	v_cvt_pk_bf16_f32 v230, v240, v241
	global_store_dwordx4 v[162:163], v[170:173], off
	global_store_dwordx4 v[162:163], v[228:231], off offset:128
	s_waitcnt lgkmcnt(0)
	v_pk_fma_f32 v[162:163], v[102:103], v[184:185], v[14:15] op_sel_hi:[1,0,1] neg_lo:[1,0,0] neg_hi:[1,0,0]
	v_pk_fma_f32 v[170:171], v[82:83], v[184:185], v[6:7] op_sel_hi:[1,0,1] neg_lo:[1,0,0] neg_hi:[1,0,0]
	v_pk_fma_f32 v[162:163], v[162:163], v[232:233], v[106:107] op_sel_hi:[1,0,1]
	v_pk_fma_f32 v[170:171], v[170:171], v[232:233], v[86:87] op_sel_hi:[1,0,1]
	s_waitcnt vmcnt(5)
	v_mov_b32_e32 v173, v182
	v_mov_b32_e32 v182, v181
	v_mov_b32_e32 v172, v180
	v_pk_mul_f32 v[180:181], v[182:183], v[170:171]
	v_pk_mul_f32 v[170:171], v[172:173], v[170:171]
	v_pk_fma_f32 v[180:181], v[172:173], v[162:163], v[180:181] neg_lo:[0,0,1] neg_hi:[0,0,1]
	v_pk_fma_f32 v[172:173], v[84:85], v[184:185], v[8:9] op_sel_hi:[1,0,1] neg_lo:[1,0,0] neg_hi:[1,0,0]
	v_pk_fma_f32 v[162:163], v[182:183], v[162:163], v[170:171]
	v_pk_fma_f32 v[170:171], v[104:105], v[184:185], v[16:17] op_sel_hi:[1,0,1] neg_lo:[1,0,0] neg_hi:[1,0,0]
	v_pk_fma_f32 v[172:173], v[172:173], v[232:233], v[88:89] op_sel_hi:[1,0,1]
	s_waitcnt vmcnt(4)
	v_mov_b32_e32 v182, v224
	v_mov_b32_e32 v183, v226
	v_mov_b32_e32 v226, v225
	v_pk_fma_f32 v[170:171], v[170:171], v[232:233], v[108:109] op_sel_hi:[1,0,1]
	v_pk_mul_f32 v[224:225], v[226:227], v[172:173]
	v_pk_mul_f32 v[172:173], v[182:183], v[172:173]
	v_pk_fma_f32 v[224:225], v[182:183], v[170:171], v[224:225] neg_lo:[0,0,1] neg_hi:[0,0,1]
	v_pk_fma_f32 v[170:171], v[226:227], v[170:171], v[172:173]
	v_pk_fma_f32 v[182:183], v[70:71], v[184:185], v[2:3] op_sel_hi:[1,0,1] neg_lo:[1,0,0] neg_hi:[1,0,0]
	v_pk_mul_f32 v[172:173], v[222:223], v[170:171] op_sel_hi:[0,1]
	v_pk_fma_f32 v[170:171], v[90:91], v[184:185], v[10:11] op_sel_hi:[1,0,1] neg_lo:[1,0,0] neg_hi:[1,0,0]
	v_pk_fma_f32 v[182:183], v[182:183], v[232:233], v[74:75] op_sel_hi:[1,0,1]
	v_pk_fma_f32 v[170:171], v[170:171], v[232:233], v[94:95] op_sel_hi:[1,0,1]
	v_pk_mul_f32 v[162:163], v[222:223], v[162:163] op_sel_hi:[0,1]
	v_pk_mul_f32 v[180:181], v[222:223], v[180:181] op_sel_hi:[0,1]
	v_pk_mul_f32 v[224:225], v[222:223], v[224:225] op_sel_hi:[0,1]
	s_waitcnt vmcnt(3)
	v_mov_b32_e32 v227, v168
	v_mov_b32_e32 v168, v167
	v_mov_b32_e32 v226, v166
	v_pk_mul_f32 v[166:167], v[168:169], v[182:183]
	s_nop 0
	v_pk_fma_f32 v[166:167], v[226:227], v[170:171], v[166:167] neg_lo:[0,0,1] neg_hi:[0,0,1]
	s_nop 0
	v_pk_mul_f32 v[228:229], v[222:223], v[166:167] op_sel_hi:[0,1]
	v_pk_mul_f32 v[166:167], v[226:227], v[182:183]
	s_nop 0
	v_pk_fma_f32 v[166:167], v[168:169], v[170:171], v[166:167]
	v_pk_fma_f32 v[168:169], v[72:73], v[184:185], v[4:5] op_sel_hi:[1,0,1] neg_lo:[1,0,0] neg_hi:[1,0,0]
	v_pk_mul_f32 v[182:183], v[222:223], v[166:167] op_sel_hi:[0,1]
	v_pk_fma_f32 v[166:167], v[92:93], v[184:185], v[12:13] op_sel_hi:[1,0,1] neg_lo:[1,0,0] neg_hi:[1,0,0]
	v_pk_fma_f32 v[168:169], v[168:169], v[232:233], v[76:77] op_sel_hi:[1,0,1]
	s_waitcnt vmcnt(2)
	v_mov_b32_e32 v171, v176
	v_mov_b32_e32 v176, v175
	v_pk_fma_f32 v[166:167], v[166:167], v[232:233], v[96:97] op_sel_hi:[1,0,1]
	v_mov_b32_e32 v170, v174
	v_pk_mul_f32 v[174:175], v[176:177], v[168:169]
	v_pk_mul_f32 v[168:169], v[170:171], v[168:169]
	v_pk_fma_f32 v[174:175], v[170:171], v[166:167], v[174:175] neg_lo:[0,0,1] neg_hi:[0,0,1]
	v_pk_fma_f32 v[166:167], v[176:177], v[166:167], v[168:169]
	v_pk_mul_f32 v[174:175], v[222:223], v[174:175] op_sel_hi:[0,1]
	v_cvt_pk_bf16_f32 v170, v162, v163
	v_lshlrev_b64 v[162:163], 10, v[164:165]
	v_pk_mul_f32 v[176:177], v[222:223], v[166:167] op_sel_hi:[0,1]
	v_cvt_pk_bf16_f32 v166, v180, v181
	v_cvt_pk_bf16_f32 v167, v224, v225
	v_cvt_pk_bf16_f32 v168, v228, v229
	v_cvt_pk_bf16_f32 v169, v174, v175
	v_lshl_add_u64 v[162:163], v[178:179], 0, v[162:163]
	v_cvt_pk_bf16_f32 v171, v172, v173
	v_cvt_pk_bf16_f32 v172, v182, v183
	v_cvt_pk_bf16_f32 v173, v176, v177
	global_store_dwordx4 v[162:163], v[166:169], off
	global_store_dwordx4 v[162:163], v[170:173], off offset:128

.LBB0_807:
	s_lshl_b32 s3, s44, 8
	v_mbcnt_lo_u32_b32 v173, -1, 0
	v_mbcnt_hi_u32_b32 v173, -1, v173
	s_add_i32 s3, s3, s76
	v_and_b32_e32 v222, 15, v173
	v_ashrrev_i32_e32 v224, 4, v173
	s_lshl_b32 s30, s42, 8
	s_or_b32 s53, s30, s72
	v_add_u32_e32 v176, s3, v222
	v_lshl_add_u32 v66, v224, 2, s53
	v_ashrrev_i32_e32 v177, 31, v176
	v_lshlrev_b64 v[198:199], 11, v[176:177]
	v_ashrrev_i32_e32 v67, 31, v66
	v_add_u32_e32 v180, 16, v176
	v_lshl_add_u64 v[68:69], s[96:97], 0, v[198:199]
	v_lshlrev_b64 v[66:67], 1, v[66:67]
	v_ashrrev_i32_e32 v181, 31, v180
	v_lshl_add_u64 v[68:69], v[68:69], 0, v[66:67]
	v_lshl_add_u64 v[178:179], s[96:97], 0, v[66:67]
	v_lshlrev_b64 v[66:67], 11, v[180:181]
	global_load_dwordx2 v[214:215], v[68:69], off
	global_load_dwordx2 v[212:213], v[68:69], off offset:32
	global_load_dwordx2 v[202:203], v[68:69], off offset:256
	global_load_dwordx2 v[182:183], v[68:69], off offset:288
	v_lshl_add_u64 v[184:185], v[178:179], 0, v[66:67]
	global_load_dwordx2 v[208:209], v[184:185], off
	global_load_dwordx2 v[204:205], v[184:185], off offset:32
	global_load_dwordx2 v[200:201], v[184:185], off offset:256
	global_load_dwordx2 v[196:197], v[184:185], off offset:288
	v_lshlrev_b32_e32 v226, 2, v222
	ds_bpermute_b32 v206, v226, v174
	ds_bpermute_b32 v210, v226, v218
	v_cndmask_b32_e64 v66, 0, 1, s[14:15]
	v_lshl_add_u32 v70, v224, 4, s81
	v_cmp_ne_u32_e64 s[36:37], 1, v66
	ds_read_b128 v[98:101], v70
	ds_read_b128 v[86:89], v70 offset:64
	ds_read_b128 v[102:105], v70 offset:1024
	ds_read_b128 v[90:93], v70 offset:1088
	ds_read_b128 v[74:77], v70 offset:512
	ds_read_b128 v[66:69], v70 offset:576
	ds_read_b128 v[78:81], v70 offset:1536
	ds_read_b128 v[70:73], v70 offset:1600
	s_andn2_b64 vcc, exec, s[14:15]
	v_lshl_add_u64 v[198:199], v[178:179], 0, v[198:199]
	s_waitcnt lgkmcnt(0)
	s_waitcnt vmcnt(7)
	v_lshlrev_b32_e32 v216, 16, v214
	v_and_b32_e32 v217, 0xffff0000, v214
	v_lshlrev_b32_e32 v214, 16, v215
	v_and_b32_e32 v215, 0xffff0000, v215
	v_pk_add_f32 v[216:217], v[216:217], v[206:207] op_sel_hi:[1,0] neg_lo:[0,1] neg_hi:[0,1]
	v_pk_add_f32 v[214:215], v[214:215], v[206:207] op_sel_hi:[1,0] neg_lo:[0,1] neg_hi:[0,1]
	v_pk_mul_f32 v[216:217], v[216:217], v[210:211] op_sel_hi:[1,0]
	v_pk_mul_f32 v[214:215], v[214:215], v[210:211] op_sel_hi:[1,0]
	v_pk_fma_f32 v[216:217], v[98:99], v[216:217], v[102:103]
	v_pk_fma_f32 v[214:215], v[100:101], v[214:215], v[104:105]
	v_pk_mul_f32 v[216:217], v[216:217], s[70:71] op_sel_hi:[1,0]
	v_pk_mul_f32 v[214:215], v[214:215], s[70:71] op_sel_hi:[1,0]
	v_pk_fma_f32 v[158:159], v[162:163], v[158:159], v[216:217]
	v_pk_fma_f32 v[160:161], v[162:163], v[160:161], v[214:215]
	s_cbranch_vccnz .LBB0_809
	v_cvt_pk_bf16_f32 v214, v158, v159
	v_cvt_pk_bf16_f32 v215, v160, v161
	global_store_dwordx2 v[198:199], v[214:215], off
.LBB0_809:
	v_mov_b32_e32 v207, v206
	s_waitcnt vmcnt(6)
	v_lshlrev_b32_e32 v214, 16, v212
	v_and_b32_e32 v215, 0xffff0000, v212
	v_lshlrev_b32_e32 v212, 16, v213
	v_and_b32_e32 v213, 0xffff0000, v213
	v_mov_b32_e32 v211, v210
	v_pk_add_f32 v[214:215], v[214:215], v[206:207] neg_lo:[0,1] neg_hi:[0,1]
	v_pk_add_f32 v[212:213], v[212:213], v[206:207] neg_lo:[0,1] neg_hi:[0,1]
	v_pk_mul_f32 v[214:215], v[214:215], v[210:211]
	v_pk_mul_f32 v[212:213], v[212:213], v[210:211]
	v_pk_fma_f32 v[214:215], v[86:87], v[214:215], v[90:91]
	v_pk_fma_f32 v[212:213], v[88:89], v[212:213], v[92:93]
	v_pk_mul_f32 v[214:215], v[214:215], s[70:71] op_sel_hi:[1,0]
	v_pk_mul_f32 v[212:213], v[212:213], s[70:71] op_sel_hi:[1,0]
	v_pk_fma_f32 v[154:155], v[162:163], v[154:155], v[214:215]
	s_and_b64 vcc, exec, s[36:37]
	v_pk_fma_f32 v[156:157], v[162:163], v[156:157], v[212:213]
	s_cbranch_vccnz .LBB0_811
	v_cvt_pk_bf16_f32 v212, v154, v155
	v_cvt_pk_bf16_f32 v213, v156, v157
	global_store_dwordx2 v[198:199], v[212:213], off offset:32
.LBB0_811:
	s_waitcnt vmcnt(5)
	v_lshlrev_b32_e32 v212, 16, v202
	v_and_b32_e32 v213, 0xffff0000, v202
	v_lshlrev_b32_e32 v202, 16, v203
	v_and_b32_e32 v203, 0xffff0000, v203
	v_pk_add_f32 v[212:213], v[212:213], v[206:207] neg_lo:[0,1] neg_hi:[0,1]
	v_pk_add_f32 v[202:203], v[202:203], v[206:207] neg_lo:[0,1] neg_hi:[0,1]
	v_pk_mul_f32 v[212:213], v[212:213], v[210:211]
	v_pk_mul_f32 v[202:203], v[202:203], v[210:211]
	v_pk_fma_f32 v[212:213], v[74:75], v[212:213], v[78:79]
	v_pk_fma_f32 v[202:203], v[76:77], v[202:203], v[80:81]
	v_pk_mul_f32 v[212:213], v[212:213], s[70:71] op_sel_hi:[1,0]
	v_pk_mul_f32 v[202:203], v[202:203], s[70:71] op_sel_hi:[1,0]
	v_pk_fma_f32 v[150:151], v[162:163], v[150:151], v[212:213]
	s_and_b64 vcc, exec, s[36:37]
	v_pk_fma_f32 v[152:153], v[162:163], v[152:153], v[202:203]
	s_cbranch_vccnz .LBB0_813
	v_cvt_pk_bf16_f32 v202, v150, v151
	v_cvt_pk_bf16_f32 v203, v152, v153
	global_store_dwordx2 v[198:199], v[202:203], off offset:256
.LBB0_813:
	s_waitcnt vmcnt(4)
	v_lshlrev_b32_e32 v202, 16, v182
	v_and_b32_e32 v203, 0xffff0000, v182
	v_lshlrev_b32_e32 v182, 16, v183
	v_and_b32_e32 v183, 0xffff0000, v183
	v_pk_add_f32 v[202:203], v[202:203], v[206:207] neg_lo:[0,1] neg_hi:[0,1]
	v_pk_add_f32 v[182:183], v[182:183], v[206:207] neg_lo:[0,1] neg_hi:[0,1]
	v_pk_mul_f32 v[202:203], v[202:203], v[210:211]
	v_pk_mul_f32 v[182:183], v[182:183], v[210:211]
	v_pk_fma_f32 v[202:203], v[66:67], v[202:203], v[70:71]
	v_pk_fma_f32 v[182:183], v[68:69], v[182:183], v[72:73]
	v_pk_mul_f32 v[202:203], v[202:203], s[70:71] op_sel_hi:[1,0]
	v_pk_mul_f32 v[182:183], v[182:183], s[70:71] op_sel_hi:[1,0]
	v_pk_fma_f32 v[146:147], v[162:163], v[146:147], v[202:203]
	s_and_b64 vcc, exec, s[36:37]
	v_pk_fma_f32 v[148:149], v[162:163], v[148:149], v[182:183]
	s_cbranch_vccnz .LBB0_815
	v_cvt_pk_bf16_f32 v182, v146, v147
	v_cvt_pk_bf16_f32 v183, v148, v149
	global_store_dwordx2 v[198:199], v[182:183], off offset:288

.LBB0_817:
	s_or_b64 exec, exec, s[42:43]
	v_add_u32_e32 v182, 32, v176
	v_ashrrev_i32_e32 v183, 31, v182
	s_waitcnt lgkmcnt(0)
	v_lshlrev_b64 v[198:199], 11, v[182:183]
	v_lshl_add_u64 v[198:199], v[178:179], 0, v[198:199]
	global_load_dwordx2 v[212:213], v[198:199], off
	global_load_dwordx2 v[210:211], v[198:199], off offset:32
	global_load_dwordx2 v[206:207], v[198:199], off offset:256
	global_load_dwordx2 v[202:203], v[198:199], off offset:288
	ds_bpermute_b32 v214, v226, v174 offset:64
	ds_bpermute_b32 v216, v226, v218 offset:64
	s_waitcnt vmcnt(7)
	v_lshlrev_b32_e32 v220, 16, v208
	v_and_b32_e32 v221, 0xffff0000, v208
	v_lshlrev_b32_e32 v208, 16, v209
	v_and_b32_e32 v209, 0xffff0000, v209
	s_waitcnt lgkmcnt(0)
	v_pk_add_f32 v[220:221], v[220:221], v[214:215] op_sel_hi:[1,0] neg_lo:[0,1] neg_hi:[0,1]
	v_pk_add_f32 v[208:209], v[208:209], v[214:215] op_sel_hi:[1,0] neg_lo:[0,1] neg_hi:[0,1]
	v_pk_mul_f32 v[220:221], v[220:221], v[216:217] op_sel_hi:[1,0]
	v_pk_mul_f32 v[208:209], v[208:209], v[216:217] op_sel_hi:[1,0]
	v_pk_fma_f32 v[220:221], v[98:99], v[220:221], v[102:103]
	v_pk_fma_f32 v[208:209], v[100:101], v[208:209], v[104:105]
	v_pk_mul_f32 v[220:221], v[220:221], s[70:71] op_sel_hi:[1,0]
	v_pk_mul_f32 v[208:209], v[208:209], s[70:71] op_sel_hi:[1,0]
	v_pk_fma_f32 v[142:143], v[162:163], v[142:143], v[220:221]
	s_and_b64 vcc, exec, s[36:37]
	v_pk_fma_f32 v[144:145], v[162:163], v[144:145], v[208:209]
	s_cbranch_vccnz .LBB0_819
	v_cvt_pk_bf16_f32 v208, v142, v143
	v_cvt_pk_bf16_f32 v209, v144, v145
	global_store_dwordx2 v[184:185], v[208:209], off
.LBB0_819:
	v_mov_b32_e32 v215, v214
	s_waitcnt vmcnt(6)
	v_lshlrev_b32_e32 v208, 16, v204
	v_and_b32_e32 v209, 0xffff0000, v204
	v_lshlrev_b32_e32 v204, 16, v205
	v_and_b32_e32 v205, 0xffff0000, v205
	v_mov_b32_e32 v217, v216
	v_pk_add_f32 v[208:209], v[208:209], v[214:215] neg_lo:[0,1] neg_hi:[0,1]
	v_pk_add_f32 v[204:205], v[204:205], v[214:215] neg_lo:[0,1] neg_hi:[0,1]
	v_pk_mul_f32 v[208:209], v[208:209], v[216:217]
	v_pk_mul_f32 v[204:205], v[204:205], v[216:217]
	v_pk_fma_f32 v[208:209], v[86:87], v[208:209], v[90:91]
	v_pk_fma_f32 v[204:205], v[88:89], v[204:205], v[92:93]
	v_pk_mul_f32 v[208:209], v[208:209], s[70:71] op_sel_hi:[1,0]
	v_pk_mul_f32 v[204:205], v[204:205], s[70:71] op_sel_hi:[1,0]
	v_pk_fma_f32 v[138:139], v[162:163], v[138:139], v[208:209]
	s_and_b64 vcc, exec, s[36:37]
	v_pk_fma_f32 v[140:141], v[162:163], v[140:141], v[204:205]
	s_cbranch_vccnz .LBB0_821
	v_cvt_pk_bf16_f32 v204, v138, v139
	v_cvt_pk_bf16_f32 v205, v140, v141
	global_store_dwordx2 v[184:185], v[204:205], off offset:32
.LBB0_821:
	s_waitcnt vmcnt(5)
	v_lshlrev_b32_e32 v204, 16, v200
	v_and_b32_e32 v205, 0xffff0000, v200
	v_lshlrev_b32_e32 v200, 16, v201
	v_and_b32_e32 v201, 0xffff0000, v201
	v_pk_add_f32 v[204:205], v[204:205], v[214:215] neg_lo:[0,1] neg_hi:[0,1]
	v_pk_add_f32 v[200:201], v[200:201], v[214:215] neg_lo:[0,1] neg_hi:[0,1]
	v_pk_mul_f32 v[204:205], v[204:205], v[216:217]
	v_pk_mul_f32 v[200:201], v[200:201], v[216:217]
	v_pk_fma_f32 v[204:205], v[74:75], v[204:205], v[78:79]
	v_pk_fma_f32 v[200:201], v[76:77], v[200:201], v[80:81]
	v_pk_mul_f32 v[204:205], v[204:205], s[70:71] op_sel_hi:[1,0]
	v_pk_mul_f32 v[200:201], v[200:201], s[70:71] op_sel_hi:[1,0]
	v_pk_fma_f32 v[134:135], v[162:163], v[134:135], v[204:205]
	s_and_b64 vcc, exec, s[36:37]
	v_pk_fma_f32 v[136:137], v[162:163], v[136:137], v[200:201]
	s_cbranch_vccnz .LBB0_823
	v_cvt_pk_bf16_f32 v200, v134, v135
	v_cvt_pk_bf16_f32 v201, v136, v137
	global_store_dwordx2 v[184:185], v[200:201], off offset:256
.LBB0_823:
	s_waitcnt vmcnt(4)
	v_lshlrev_b32_e32 v200, 16, v196
	v_and_b32_e32 v201, 0xffff0000, v196
	v_lshlrev_b32_e32 v196, 16, v197
	v_and_b32_e32 v197, 0xffff0000, v197
	v_pk_add_f32 v[200:201], v[200:201], v[214:215] neg_lo:[0,1] neg_hi:[0,1]
	v_pk_add_f32 v[196:197], v[196:197], v[214:215] neg_lo:[0,1] neg_hi:[0,1]
	v_pk_mul_f32 v[200:201], v[200:201], v[216:217]
	v_pk_mul_f32 v[196:197], v[196:197], v[216:217]
	v_pk_fma_f32 v[200:201], v[66:67], v[200:201], v[70:71]
	v_pk_fma_f32 v[196:197], v[68:69], v[196:197], v[72:73]
	v_pk_mul_f32 v[200:201], v[200:201], s[70:71] op_sel_hi:[1,0]
	v_pk_mul_f32 v[196:197], v[196:197], s[70:71] op_sel_hi:[1,0]
	v_pk_fma_f32 v[130:131], v[162:163], v[130:131], v[200:201]
	s_and_b64 vcc, exec, s[36:37]
	v_pk_fma_f32 v[132:133], v[162:163], v[132:133], v[196:197]
	s_cbranch_vccnz .LBB0_825
	v_cvt_pk_bf16_f32 v196, v130, v131
	v_cvt_pk_bf16_f32 v197, v132, v133
	global_store_dwordx2 v[184:185], v[196:197], off offset:288

.LBB0_827:
	s_or_b64 exec, exec, s[42:43]
	v_add_u32_e32 v180, 48, v176
	v_ashrrev_i32_e32 v181, 31, v180
	v_lshlrev_b64 v[184:185], 11, v[180:181]
	v_lshl_add_u64 v[184:185], v[178:179], 0, v[184:185]
	global_load_dwordx2 v[214:215], v[184:185], off
	global_load_dwordx2 v[208:209], v[184:185], off offset:32
	global_load_dwordx2 v[204:205], v[184:185], off offset:256
	global_load_dwordx2 v[200:201], v[184:185], off offset:288
	s_waitcnt lgkmcnt(0)
	ds_bpermute_b32 v196, v226, v174 offset:128
	ds_bpermute_b32 v216, v226, v218 offset:128
	s_waitcnt vmcnt(7)
	v_lshlrev_b32_e32 v220, 16, v212
	v_and_b32_e32 v221, 0xffff0000, v212
	v_lshlrev_b32_e32 v212, 16, v213
	v_and_b32_e32 v213, 0xffff0000, v213
	s_waitcnt lgkmcnt(1)
	v_pk_add_f32 v[220:221], v[220:221], v[196:197] op_sel_hi:[1,0] neg_lo:[0,1] neg_hi:[0,1]
	v_pk_add_f32 v[212:213], v[212:213], v[196:197] op_sel_hi:[1,0] neg_lo:[0,1] neg_hi:[0,1]
	s_waitcnt lgkmcnt(0)
	v_pk_mul_f32 v[220:221], v[220:221], v[216:217] op_sel_hi:[1,0]
	v_pk_mul_f32 v[212:213], v[212:213], v[216:217] op_sel_hi:[1,0]
	v_pk_fma_f32 v[220:221], v[98:99], v[220:221], v[102:103]
	v_pk_fma_f32 v[212:213], v[100:101], v[212:213], v[104:105]
	v_pk_mul_f32 v[220:221], v[220:221], s[70:71] op_sel_hi:[1,0]
	v_pk_mul_f32 v[212:213], v[212:213], s[70:71] op_sel_hi:[1,0]
	v_pk_fma_f32 v[126:127], v[162:163], v[126:127], v[220:221]
	s_and_b64 vcc, exec, s[36:37]
	v_pk_fma_f32 v[128:129], v[162:163], v[128:129], v[212:213]
	s_cbranch_vccnz .LBB0_829
	v_cvt_pk_bf16_f32 v212, v126, v127
	v_cvt_pk_bf16_f32 v213, v128, v129
	global_store_dwordx2 v[198:199], v[212:213], off
.LBB0_829:
	v_mov_b32_e32 v197, v196
	s_waitcnt vmcnt(6)
	v_lshlrev_b32_e32 v212, 16, v210
	v_and_b32_e32 v213, 0xffff0000, v210
	v_lshlrev_b32_e32 v210, 16, v211
	v_and_b32_e32 v211, 0xffff0000, v211
	v_mov_b32_e32 v217, v216
	v_pk_add_f32 v[212:213], v[212:213], v[196:197] neg_lo:[0,1] neg_hi:[0,1]
	v_pk_add_f32 v[210:211], v[210:211], v[196:197] neg_lo:[0,1] neg_hi:[0,1]
	v_pk_mul_f32 v[212:213], v[212:213], v[216:217]
	v_pk_mul_f32 v[210:211], v[210:211], v[216:217]
	v_pk_fma_f32 v[212:213], v[86:87], v[212:213], v[90:91]
	v_pk_fma_f32 v[210:211], v[88:89], v[210:211], v[92:93]
	v_pk_mul_f32 v[212:213], v[212:213], s[70:71] op_sel_hi:[1,0]
	v_pk_mul_f32 v[210:211], v[210:211], s[70:71] op_sel_hi:[1,0]
	v_pk_fma_f32 v[122:123], v[162:163], v[122:123], v[212:213]
	s_and_b64 vcc, exec, s[36:37]
	v_pk_fma_f32 v[124:125], v[162:163], v[124:125], v[210:211]
	s_cbranch_vccnz .LBB0_831
	v_cvt_pk_bf16_f32 v210, v122, v123
	v_cvt_pk_bf16_f32 v211, v124, v125
	global_store_dwordx2 v[198:199], v[210:211], off offset:32
.LBB0_831:
	s_waitcnt vmcnt(5)
	v_lshlrev_b32_e32 v210, 16, v206
	v_and_b32_e32 v211, 0xffff0000, v206
	v_lshlrev_b32_e32 v206, 16, v207
	v_and_b32_e32 v207, 0xffff0000, v207
	v_pk_add_f32 v[210:211], v[210:211], v[196:197] neg_lo:[0,1] neg_hi:[0,1]
	v_pk_add_f32 v[206:207], v[206:207], v[196:197] neg_lo:[0,1] neg_hi:[0,1]
	v_pk_mul_f32 v[210:211], v[210:211], v[216:217]
	v_pk_mul_f32 v[206:207], v[206:207], v[216:217]
	v_pk_fma_f32 v[210:211], v[74:75], v[210:211], v[78:79]
	v_pk_fma_f32 v[206:207], v[76:77], v[206:207], v[80:81]
	v_pk_mul_f32 v[210:211], v[210:211], s[70:71] op_sel_hi:[1,0]
	v_pk_mul_f32 v[206:207], v[206:207], s[70:71] op_sel_hi:[1,0]
	v_pk_fma_f32 v[118:119], v[162:163], v[118:119], v[210:211]
	s_and_b64 vcc, exec, s[36:37]
	v_pk_fma_f32 v[120:121], v[162:163], v[120:121], v[206:207]
	s_cbranch_vccnz .LBB0_833
	v_cvt_pk_bf16_f32 v206, v118, v119
	v_cvt_pk_bf16_f32 v207, v120, v121
	global_store_dwordx2 v[198:199], v[206:207], off offset:256
.LBB0_833:
	s_waitcnt vmcnt(4)
	v_lshlrev_b32_e32 v206, 16, v202
	v_and_b32_e32 v207, 0xffff0000, v202
	v_lshlrev_b32_e32 v202, 16, v203
	v_and_b32_e32 v203, 0xffff0000, v203
	v_pk_add_f32 v[206:207], v[206:207], v[196:197] neg_lo:[0,1] neg_hi:[0,1]
	v_pk_add_f32 v[196:197], v[202:203], v[196:197] neg_lo:[0,1] neg_hi:[0,1]
	v_pk_mul_f32 v[206:207], v[206:207], v[216:217]
	v_pk_mul_f32 v[196:197], v[196:197], v[216:217]
	v_pk_fma_f32 v[206:207], v[66:67], v[206:207], v[70:71]
	v_pk_fma_f32 v[196:197], v[68:69], v[196:197], v[72:73]
	v_pk_mul_f32 v[206:207], v[206:207], s[70:71] op_sel_hi:[1,0]
	v_pk_mul_f32 v[196:197], v[196:197], s[70:71] op_sel_hi:[1,0]
	v_pk_fma_f32 v[114:115], v[162:163], v[114:115], v[206:207]
	s_and_b64 vcc, exec, s[36:37]
	v_pk_fma_f32 v[116:117], v[162:163], v[116:117], v[196:197]
	s_cbranch_vccnz .LBB0_835
	v_cvt_pk_bf16_f32 v196, v114, v115
	v_cvt_pk_bf16_f32 v197, v116, v117
	global_store_dwordx2 v[198:199], v[196:197], off offset:288

.LBB0_837:
	s_or_b64 exec, exec, s[42:43]
	v_add_u32_e32 v182, 0x80, v176
	v_ashrrev_i32_e32 v183, 31, v182
	v_lshlrev_b64 v[196:197], 11, v[182:183]
	v_lshl_add_u64 v[196:197], v[178:179], 0, v[196:197]
	global_load_dwordx2 v[216:217], v[196:197], off
	global_load_dwordx2 v[210:211], v[196:197], off offset:32
	global_load_dwordx2 v[206:207], v[196:197], off offset:256
	s_waitcnt lgkmcnt(0)
	global_load_dwordx2 v[198:199], v[196:197], off offset:288
	ds_bpermute_b32 v174, v226, v174 offset:192
	ds_bpermute_b32 v202, v226, v218 offset:192
	s_waitcnt vmcnt(7)
	v_lshlrev_b32_e32 v212, 16, v214
	v_and_b32_e32 v213, 0xffff0000, v214
	v_lshlrev_b32_e32 v214, 16, v215
	s_waitcnt lgkmcnt(0)
	v_pk_add_f32 v[212:213], v[212:213], v[174:175] op_sel_hi:[1,0] neg_lo:[0,1] neg_hi:[0,1]
	v_and_b32_e32 v215, 0xffff0000, v215
	v_pk_mul_f32 v[212:213], v[212:213], v[202:203] op_sel_hi:[1,0]
	s_and_b64 vcc, exec, s[36:37]
	v_pk_fma_f32 v[212:213], v[98:99], v[212:213], v[102:103]
	s_nop 0
	v_pk_mul_f32 v[212:213], v[212:213], s[70:71] op_sel_hi:[1,0]
	s_nop 0
	v_pk_fma_f32 v[110:111], v[162:163], v[110:111], v[212:213]
	v_pk_add_f32 v[212:213], v[214:215], v[174:175] op_sel_hi:[1,0] neg_lo:[0,1] neg_hi:[0,1]
	s_nop 0
	v_pk_mul_f32 v[212:213], v[212:213], v[202:203] op_sel_hi:[1,0]
	s_nop 0
	v_pk_fma_f32 v[212:213], v[100:101], v[212:213], v[104:105]
	s_nop 0
	v_pk_mul_f32 v[212:213], v[212:213], s[70:71] op_sel_hi:[1,0]
	s_nop 0
	v_pk_fma_f32 v[112:113], v[162:163], v[112:113], v[212:213]
	s_cbranch_vccnz .LBB0_839
	v_cvt_pk_bf16_f32 v212, v110, v111
	v_cvt_pk_bf16_f32 v213, v112, v113
	global_store_dwordx2 v[184:185], v[212:213], off
.LBB0_839:
	v_mov_b32_e32 v175, v174
	s_waitcnt vmcnt(6)
	v_lshlrev_b32_e32 v212, 16, v208
	v_and_b32_e32 v213, 0xffff0000, v208
	v_lshlrev_b32_e32 v208, 16, v209
	v_and_b32_e32 v209, 0xffff0000, v209
	v_mov_b32_e32 v203, v202
	v_pk_add_f32 v[212:213], v[212:213], v[174:175] neg_lo:[0,1] neg_hi:[0,1]
	v_pk_add_f32 v[208:209], v[208:209], v[174:175] neg_lo:[0,1] neg_hi:[0,1]
	v_pk_mul_f32 v[212:213], v[212:213], v[202:203]
	v_pk_mul_f32 v[208:209], v[208:209], v[202:203]
	v_pk_fma_f32 v[212:213], v[86:87], v[212:213], v[90:91]
	v_pk_fma_f32 v[208:209], v[88:89], v[208:209], v[92:93]
	v_pk_mul_f32 v[212:213], v[212:213], s[70:71] op_sel_hi:[1,0]
	v_pk_mul_f32 v[208:209], v[208:209], s[70:71] op_sel_hi:[1,0]
	v_pk_fma_f32 v[106:107], v[162:163], v[106:107], v[212:213]
	s_and_b64 vcc, exec, s[36:37]
	v_pk_fma_f32 v[108:109], v[162:163], v[108:109], v[208:209]
	s_cbranch_vccnz .LBB0_841
	v_cvt_pk_bf16_f32 v208, v106, v107
	v_cvt_pk_bf16_f32 v209, v108, v109
	global_store_dwordx2 v[184:185], v[208:209], off offset:32
.LBB0_841:
	s_waitcnt vmcnt(5)
	v_lshlrev_b32_e32 v208, 16, v204
	v_and_b32_e32 v209, 0xffff0000, v204
	v_lshlrev_b32_e32 v204, 16, v205
	v_and_b32_e32 v205, 0xffff0000, v205
	v_pk_add_f32 v[208:209], v[208:209], v[174:175] neg_lo:[0,1] neg_hi:[0,1]
	v_pk_add_f32 v[204:205], v[204:205], v[174:175] neg_lo:[0,1] neg_hi:[0,1]
	v_pk_mul_f32 v[208:209], v[208:209], v[202:203]
	v_pk_mul_f32 v[204:205], v[204:205], v[202:203]
	v_pk_fma_f32 v[208:209], v[74:75], v[208:209], v[78:79]
	v_pk_fma_f32 v[204:205], v[76:77], v[204:205], v[80:81]
	v_pk_mul_f32 v[208:209], v[208:209], s[70:71] op_sel_hi:[1,0]
	v_pk_mul_f32 v[204:205], v[204:205], s[70:71] op_sel_hi:[1,0]
	v_pk_fma_f32 v[94:95], v[162:163], v[94:95], v[208:209]
	s_and_b64 vcc, exec, s[36:37]
	v_pk_fma_f32 v[96:97], v[162:163], v[96:97], v[204:205]
	s_cbranch_vccnz .LBB0_843
	v_cvt_pk_bf16_f32 v204, v94, v95
	v_cvt_pk_bf16_f32 v205, v96, v97
	global_store_dwordx2 v[184:185], v[204:205], off offset:256
.LBB0_843:
	s_waitcnt vmcnt(4)
	v_lshlrev_b32_e32 v204, 16, v200
	v_and_b32_e32 v205, 0xffff0000, v200
	v_lshlrev_b32_e32 v200, 16, v201
	v_and_b32_e32 v201, 0xffff0000, v201
	v_pk_add_f32 v[204:205], v[204:205], v[174:175] neg_lo:[0,1] neg_hi:[0,1]
	v_pk_add_f32 v[174:175], v[200:201], v[174:175] neg_lo:[0,1] neg_hi:[0,1]
	v_pk_mul_f32 v[204:205], v[204:205], v[202:203]
	v_pk_mul_f32 v[174:175], v[174:175], v[202:203]
	v_pk_fma_f32 v[204:205], v[66:67], v[204:205], v[70:71]
	v_pk_fma_f32 v[174:175], v[68:69], v[174:175], v[72:73]
	v_pk_mul_f32 v[204:205], v[204:205], s[70:71] op_sel_hi:[1,0]
	v_pk_mul_f32 v[174:175], v[174:175], s[70:71] op_sel_hi:[1,0]
	v_pk_fma_f32 v[82:83], v[162:163], v[82:83], v[204:205]
	s_and_b64 vcc, exec, s[36:37]
	v_pk_fma_f32 v[84:85], v[162:163], v[84:85], v[174:175]
	s_cbranch_vccnz .LBB0_845
	v_cvt_pk_bf16_f32 v174, v82, v83
	v_cvt_pk_bf16_f32 v175, v84, v85
	global_store_dwordx2 v[184:185], v[174:175], off offset:288

.LBB0_847:
	s_or_b64 exec, exec, s[42:43]
	v_add_u32_e32 v174, 0x90, v176
	v_ashrrev_i32_e32 v175, 31, v174
	v_lshlrev_b64 v[180:181], 11, v[174:175]
	v_lshl_add_u64 v[180:181], v[178:179], 0, v[180:181]
	global_load_dwordx2 v[212:213], v[180:181], off
	global_load_dwordx2 v[208:209], v[180:181], off offset:32
	global_load_dwordx2 v[202:203], v[180:181], off offset:256
	s_waitcnt lgkmcnt(0)
	global_load_dwordx2 v[184:185], v[180:181], off offset:288
	ds_bpermute_b32 v200, v226, v172
	ds_bpermute_b32 v204, v226, v189
	s_waitcnt vmcnt(7)
	v_lshlrev_b32_e32 v214, 16, v216
	v_and_b32_e32 v215, 0xffff0000, v216
	v_lshlrev_b32_e32 v216, 16, v217
	s_waitcnt lgkmcnt(0)
	v_pk_add_f32 v[214:215], v[214:215], v[200:201] op_sel_hi:[1,0] neg_lo:[0,1] neg_hi:[0,1]
	v_and_b32_e32 v217, 0xffff0000, v217
	v_pk_mul_f32 v[214:215], v[214:215], v[204:205] op_sel_hi:[1,0]
	s_and_b64 vcc, exec, s[36:37]
	v_pk_fma_f32 v[214:215], v[98:99], v[214:215], v[102:103]
	s_nop 0
	v_pk_mul_f32 v[214:215], v[214:215], s[70:71] op_sel_hi:[1,0]
	s_nop 0
	v_pk_fma_f32 v[62:63], v[162:163], v[62:63], v[214:215]
	v_pk_add_f32 v[214:215], v[216:217], v[200:201] op_sel_hi:[1,0] neg_lo:[0,1] neg_hi:[0,1]
	s_nop 0
	v_pk_mul_f32 v[214:215], v[214:215], v[204:205] op_sel_hi:[1,0]
	s_nop 0
	v_pk_fma_f32 v[214:215], v[100:101], v[214:215], v[104:105]
	s_nop 0
	v_pk_mul_f32 v[214:215], v[214:215], s[70:71] op_sel_hi:[1,0]
	s_nop 0
	v_pk_fma_f32 v[64:65], v[162:163], v[64:65], v[214:215]
	s_cbranch_vccnz .LBB0_849
	v_cvt_pk_bf16_f32 v214, v62, v63
	v_cvt_pk_bf16_f32 v215, v64, v65
	global_store_dwordx2 v[196:197], v[214:215], off
.LBB0_849:
	v_mov_b32_e32 v201, v200
	s_waitcnt vmcnt(6)
	v_lshlrev_b32_e32 v214, 16, v210
	v_and_b32_e32 v215, 0xffff0000, v210
	v_lshlrev_b32_e32 v210, 16, v211
	v_and_b32_e32 v211, 0xffff0000, v211
	v_mov_b32_e32 v205, v204
	v_pk_add_f32 v[214:215], v[214:215], v[200:201] neg_lo:[0,1] neg_hi:[0,1]
	v_pk_add_f32 v[210:211], v[210:211], v[200:201] neg_lo:[0,1] neg_hi:[0,1]
	v_pk_mul_f32 v[214:215], v[214:215], v[204:205]
	v_pk_mul_f32 v[210:211], v[210:211], v[204:205]
	v_pk_fma_f32 v[214:215], v[86:87], v[214:215], v[90:91]
	v_pk_fma_f32 v[210:211], v[88:89], v[210:211], v[92:93]
	v_pk_mul_f32 v[214:215], v[214:215], s[70:71] op_sel_hi:[1,0]
	v_pk_mul_f32 v[210:211], v[210:211], s[70:71] op_sel_hi:[1,0]
	v_pk_fma_f32 v[58:59], v[162:163], v[58:59], v[214:215]
	s_and_b64 vcc, exec, s[36:37]
	v_pk_fma_f32 v[60:61], v[162:163], v[60:61], v[210:211]
	s_cbranch_vccnz .LBB0_851
	v_cvt_pk_bf16_f32 v210, v58, v59
	v_cvt_pk_bf16_f32 v211, v60, v61
	global_store_dwordx2 v[196:197], v[210:211], off offset:32
.LBB0_851:
	s_waitcnt vmcnt(5)
	v_lshlrev_b32_e32 v210, 16, v206
	v_and_b32_e32 v211, 0xffff0000, v206
	v_lshlrev_b32_e32 v206, 16, v207
	v_and_b32_e32 v207, 0xffff0000, v207
	v_pk_add_f32 v[210:211], v[210:211], v[200:201] neg_lo:[0,1] neg_hi:[0,1]
	v_pk_add_f32 v[206:207], v[206:207], v[200:201] neg_lo:[0,1] neg_hi:[0,1]
	v_pk_mul_f32 v[210:211], v[210:211], v[204:205]
	v_pk_mul_f32 v[206:207], v[206:207], v[204:205]
	v_pk_fma_f32 v[210:211], v[74:75], v[210:211], v[78:79]
	v_pk_fma_f32 v[206:207], v[76:77], v[206:207], v[80:81]
	v_pk_mul_f32 v[210:211], v[210:211], s[70:71] op_sel_hi:[1,0]
	v_pk_mul_f32 v[206:207], v[206:207], s[70:71] op_sel_hi:[1,0]
	v_pk_fma_f32 v[54:55], v[162:163], v[54:55], v[210:211]
	s_and_b64 vcc, exec, s[36:37]
	v_pk_fma_f32 v[56:57], v[162:163], v[56:57], v[206:207]
	s_cbranch_vccnz .LBB0_853
	v_cvt_pk_bf16_f32 v206, v54, v55
	v_cvt_pk_bf16_f32 v207, v56, v57
	global_store_dwordx2 v[196:197], v[206:207], off offset:256
.LBB0_853:
	s_waitcnt vmcnt(4)
	v_lshlrev_b32_e32 v206, 16, v198
	v_and_b32_e32 v207, 0xffff0000, v198
	v_lshlrev_b32_e32 v198, 16, v199
	v_and_b32_e32 v199, 0xffff0000, v199
	v_pk_add_f32 v[206:207], v[206:207], v[200:201] neg_lo:[0,1] neg_hi:[0,1]
	v_pk_add_f32 v[198:199], v[198:199], v[200:201] neg_lo:[0,1] neg_hi:[0,1]
	v_pk_mul_f32 v[206:207], v[206:207], v[204:205]
	v_pk_mul_f32 v[198:199], v[198:199], v[204:205]
	v_pk_fma_f32 v[206:207], v[66:67], v[206:207], v[70:71]
	v_pk_fma_f32 v[198:199], v[68:69], v[198:199], v[72:73]
	v_pk_mul_f32 v[206:207], v[206:207], s[70:71] op_sel_hi:[1,0]
	v_pk_mul_f32 v[198:199], v[198:199], s[70:71] op_sel_hi:[1,0]
	v_pk_fma_f32 v[50:51], v[162:163], v[50:51], v[206:207]
	s_and_b64 vcc, exec, s[36:37]
	v_pk_fma_f32 v[52:53], v[162:163], v[52:53], v[198:199]
	s_cbranch_vccnz .LBB0_855
	v_cvt_pk_bf16_f32 v198, v50, v51
	v_cvt_pk_bf16_f32 v199, v52, v53
	global_store_dwordx2 v[196:197], v[198:199], off offset:288

.LBB0_857:
	s_or_b64 exec, exec, s[42:43]
	v_add_u32_e32 v200, 0xa0, v176
	v_ashrrev_i32_e32 v201, 31, v200
	v_lshlrev_b64 v[182:183], 11, v[200:201]
	v_lshl_add_u64 v[204:205], v[178:179], 0, v[182:183]
	global_load_dwordx2 v[214:215], v[204:205], off
	s_waitcnt lgkmcnt(0)
	global_load_dwordx2 v[198:199], v[204:205], off offset:32
	global_load_dwordx2 v[182:183], v[204:205], off offset:256
	global_load_dwordx2 v[196:197], v[204:205], off offset:288
	v_add_u32_e32 v177, 64, v226
	ds_bpermute_b32 v206, v177, v172
	ds_bpermute_b32 v210, v177, v189
	s_waitcnt vmcnt(7)
	v_lshlrev_b32_e32 v216, 16, v212
	v_and_b32_e32 v217, 0xffff0000, v212
	v_lshlrev_b32_e32 v212, 16, v213
	v_and_b32_e32 v213, 0xffff0000, v213
	s_waitcnt lgkmcnt(0)
	v_pk_add_f32 v[216:217], v[216:217], v[206:207] op_sel_hi:[1,0] neg_lo:[0,1] neg_hi:[0,1]
	v_pk_add_f32 v[212:213], v[212:213], v[206:207] op_sel_hi:[1,0] neg_lo:[0,1] neg_hi:[0,1]
	v_pk_mul_f32 v[216:217], v[216:217], v[210:211] op_sel_hi:[1,0]
	v_pk_mul_f32 v[212:213], v[212:213], v[210:211] op_sel_hi:[1,0]
	v_pk_fma_f32 v[216:217], v[98:99], v[216:217], v[102:103]
	v_pk_fma_f32 v[212:213], v[100:101], v[212:213], v[104:105]
	v_pk_mul_f32 v[216:217], v[216:217], s[70:71] op_sel_hi:[1,0]
	v_pk_mul_f32 v[212:213], v[212:213], s[70:71] op_sel_hi:[1,0]
	v_pk_fma_f32 v[46:47], v[162:163], v[46:47], v[216:217]
	s_and_b64 vcc, exec, s[36:37]
	v_pk_fma_f32 v[48:49], v[162:163], v[48:49], v[212:213]
	s_cbranch_vccnz .LBB0_859
	v_cvt_pk_bf16_f32 v212, v46, v47
	v_cvt_pk_bf16_f32 v213, v48, v49
	global_store_dwordx2 v[180:181], v[212:213], off
.LBB0_859:
	v_mov_b32_e32 v207, v206
	s_waitcnt vmcnt(6)
	v_lshlrev_b32_e32 v212, 16, v208
	v_and_b32_e32 v213, 0xffff0000, v208
	v_lshlrev_b32_e32 v208, 16, v209
	v_and_b32_e32 v209, 0xffff0000, v209
	v_mov_b32_e32 v211, v210
	v_pk_add_f32 v[212:213], v[212:213], v[206:207] neg_lo:[0,1] neg_hi:[0,1]
	v_pk_add_f32 v[208:209], v[208:209], v[206:207] neg_lo:[0,1] neg_hi:[0,1]
	v_pk_mul_f32 v[212:213], v[212:213], v[210:211]
	v_pk_mul_f32 v[208:209], v[208:209], v[210:211]
	v_pk_fma_f32 v[212:213], v[86:87], v[212:213], v[90:91]
	v_pk_fma_f32 v[208:209], v[88:89], v[208:209], v[92:93]
	v_pk_mul_f32 v[212:213], v[212:213], s[70:71] op_sel_hi:[1,0]
	v_pk_mul_f32 v[208:209], v[208:209], s[70:71] op_sel_hi:[1,0]
	v_pk_fma_f32 v[42:43], v[162:163], v[42:43], v[212:213]
	s_and_b64 vcc, exec, s[36:37]
	v_pk_fma_f32 v[44:45], v[162:163], v[44:45], v[208:209]
	s_cbranch_vccnz .LBB0_861
	v_cvt_pk_bf16_f32 v208, v42, v43
	v_cvt_pk_bf16_f32 v209, v44, v45
	global_store_dwordx2 v[180:181], v[208:209], off offset:32
.LBB0_861:
	s_waitcnt vmcnt(5)
	v_lshlrev_b32_e32 v208, 16, v202
	v_and_b32_e32 v209, 0xffff0000, v202
	v_lshlrev_b32_e32 v202, 16, v203
	v_and_b32_e32 v203, 0xffff0000, v203
	v_pk_add_f32 v[208:209], v[208:209], v[206:207] neg_lo:[0,1] neg_hi:[0,1]
	v_pk_add_f32 v[202:203], v[202:203], v[206:207] neg_lo:[0,1] neg_hi:[0,1]
	v_pk_mul_f32 v[208:209], v[208:209], v[210:211]
	v_pk_mul_f32 v[202:203], v[202:203], v[210:211]
	v_pk_fma_f32 v[208:209], v[74:75], v[208:209], v[78:79]
	v_pk_fma_f32 v[202:203], v[76:77], v[202:203], v[80:81]
	v_pk_mul_f32 v[208:209], v[208:209], s[70:71] op_sel_hi:[1,0]
	v_pk_mul_f32 v[202:203], v[202:203], s[70:71] op_sel_hi:[1,0]
	v_pk_fma_f32 v[38:39], v[162:163], v[38:39], v[208:209]
	s_and_b64 vcc, exec, s[36:37]
	v_pk_fma_f32 v[40:41], v[162:163], v[40:41], v[202:203]
	s_cbranch_vccnz .LBB0_863
	v_cvt_pk_bf16_f32 v202, v38, v39
	v_cvt_pk_bf16_f32 v203, v40, v41
	global_store_dwordx2 v[180:181], v[202:203], off offset:256
.LBB0_863:
	s_waitcnt vmcnt(4)
	v_lshlrev_b32_e32 v202, 16, v184
	v_and_b32_e32 v203, 0xffff0000, v184
	v_lshlrev_b32_e32 v184, 16, v185
	v_and_b32_e32 v185, 0xffff0000, v185
	v_pk_add_f32 v[202:203], v[202:203], v[206:207] neg_lo:[0,1] neg_hi:[0,1]
	v_pk_add_f32 v[184:185], v[184:185], v[206:207] neg_lo:[0,1] neg_hi:[0,1]
	v_pk_mul_f32 v[202:203], v[202:203], v[210:211]
	v_pk_mul_f32 v[184:185], v[184:185], v[210:211]
	v_pk_fma_f32 v[202:203], v[66:67], v[202:203], v[70:71]
	v_pk_fma_f32 v[184:185], v[68:69], v[184:185], v[72:73]
	v_pk_mul_f32 v[202:203], v[202:203], s[70:71] op_sel_hi:[1,0]
	v_pk_mul_f32 v[184:185], v[184:185], s[70:71] op_sel_hi:[1,0]
	v_pk_fma_f32 v[34:35], v[162:163], v[34:35], v[202:203]
	s_and_b64 vcc, exec, s[36:37]
	v_pk_fma_f32 v[36:37], v[162:163], v[36:37], v[184:185]
	s_cbranch_vccnz .LBB0_865
	v_cvt_pk_bf16_f32 v184, v34, v35
	v_cvt_pk_bf16_f32 v185, v36, v37
	global_store_dwordx2 v[180:181], v[184:185], off offset:288

.LBB0_867:
	s_or_b64 exec, exec, s[42:43]
	v_add_u32_e32 v202, 0xb0, v176
	v_ashrrev_i32_e32 v203, 31, v202
	v_lshlrev_b64 v[174:175], 11, v[202:203]
	v_lshl_add_u64 v[206:207], v[178:179], 0, v[174:175]
	global_load_dwordx2 v[216:217], v[206:207], off
	global_load_dwordx2 v[212:213], v[206:207], off offset:32
	global_load_dwordx2 v[210:211], v[206:207], off offset:256
	global_load_dwordx2 v[208:209], v[206:207], off offset:288
	v_add_u32_e32 v174, 0x80, v226
	ds_bpermute_b32 v218, v174, v172
	ds_bpermute_b32 v220, v174, v189
	s_waitcnt vmcnt(7)
	v_lshlrev_b32_e32 v174, 16, v214
	v_and_b32_e32 v175, 0xffff0000, v214
	v_lshlrev_b32_e32 v176, 16, v215
	s_waitcnt lgkmcnt(0)
	v_pk_add_f32 v[174:175], v[174:175], v[218:219] op_sel_hi:[1,0] neg_lo:[0,1] neg_hi:[0,1]
	v_and_b32_e32 v177, 0xffff0000, v215
	v_pk_mul_f32 v[174:175], v[174:175], v[220:221] op_sel_hi:[1,0]
	s_and_b64 vcc, exec, s[36:37]
	v_pk_fma_f32 v[174:175], v[98:99], v[174:175], v[102:103]
	s_nop 0
	v_pk_mul_f32 v[174:175], v[174:175], s[70:71] op_sel_hi:[1,0]
	s_nop 0
	v_pk_fma_f32 v[174:175], v[162:163], v[30:31], v[174:175]
	v_pk_add_f32 v[30:31], v[176:177], v[218:219] op_sel_hi:[1,0] neg_lo:[0,1] neg_hi:[0,1]
	s_nop 0
	v_pk_mul_f32 v[30:31], v[30:31], v[220:221] op_sel_hi:[1,0]
	s_nop 0
	v_pk_fma_f32 v[30:31], v[100:101], v[30:31], v[104:105]
	s_nop 0
	v_pk_mul_f32 v[30:31], v[30:31], s[70:71] op_sel_hi:[1,0]
	s_nop 0
	v_pk_fma_f32 v[176:177], v[162:163], v[32:33], v[30:31]
	s_cbranch_vccnz .LBB0_869
	v_cvt_pk_bf16_f32 v30, v174, v175
	v_cvt_pk_bf16_f32 v31, v176, v177
	global_store_dwordx2 v[204:205], v[30:31], off
.LBB0_869:
	v_mov_b32_e32 v219, v218
	s_waitcnt vmcnt(6)
	v_lshlrev_b32_e32 v30, 16, v198
	v_and_b32_e32 v31, 0xffff0000, v198
	v_mov_b32_e32 v221, v220
	v_pk_add_f32 v[30:31], v[30:31], v[218:219] neg_lo:[0,1] neg_hi:[0,1]
	v_lshlrev_b32_e32 v32, 16, v199
	v_pk_mul_f32 v[30:31], v[30:31], v[220:221]
	v_and_b32_e32 v33, 0xffff0000, v199
	v_pk_fma_f32 v[30:31], v[86:87], v[30:31], v[90:91]
	s_and_b64 vcc, exec, s[36:37]
	v_pk_mul_f32 v[30:31], v[30:31], s[70:71] op_sel_hi:[1,0]
	s_nop 0
	v_pk_fma_f32 v[178:179], v[162:163], v[26:27], v[30:31]
	v_pk_add_f32 v[26:27], v[32:33], v[218:219] neg_lo:[0,1] neg_hi:[0,1]
	s_nop 0
	v_pk_mul_f32 v[26:27], v[26:27], v[220:221]
	s_nop 0
	v_pk_fma_f32 v[26:27], v[88:89], v[26:27], v[92:93]
	s_nop 0
	v_pk_mul_f32 v[26:27], v[26:27], s[70:71] op_sel_hi:[1,0]
	s_nop 0
	v_pk_fma_f32 v[180:181], v[162:163], v[28:29], v[26:27]
	s_cbranch_vccnz .LBB0_871
	v_cvt_pk_bf16_f32 v26, v178, v179
	v_cvt_pk_bf16_f32 v27, v180, v181
	global_store_dwordx2 v[204:205], v[26:27], off offset:32
.LBB0_871:
	s_waitcnt vmcnt(5)
	v_lshlrev_b32_e32 v26, 16, v182
	v_and_b32_e32 v27, 0xffff0000, v182
	v_pk_add_f32 v[26:27], v[26:27], v[218:219] neg_lo:[0,1] neg_hi:[0,1]
	v_lshlrev_b32_e32 v28, 16, v183
	v_pk_mul_f32 v[26:27], v[26:27], v[220:221]
	v_and_b32_e32 v29, 0xffff0000, v183
	v_pk_fma_f32 v[26:27], v[74:75], v[26:27], v[78:79]
	s_and_b64 vcc, exec, s[36:37]
	v_pk_mul_f32 v[26:27], v[26:27], s[70:71] op_sel_hi:[1,0]
	s_nop 0
	v_pk_fma_f32 v[182:183], v[162:163], v[22:23], v[26:27]
	v_pk_add_f32 v[22:23], v[28:29], v[218:219] neg_lo:[0,1] neg_hi:[0,1]
	s_nop 0
	v_pk_mul_f32 v[22:23], v[22:23], v[220:221]
	s_nop 0
	v_pk_fma_f32 v[22:23], v[76:77], v[22:23], v[80:81]
	s_nop 0
	v_pk_mul_f32 v[22:23], v[22:23], s[70:71] op_sel_hi:[1,0]
	s_nop 0
	v_pk_fma_f32 v[184:185], v[162:163], v[24:25], v[22:23]
	s_cbranch_vccnz .LBB0_873
	v_cvt_pk_bf16_f32 v22, v182, v183
	v_cvt_pk_bf16_f32 v23, v184, v185
	global_store_dwordx2 v[204:205], v[22:23], off offset:256
.LBB0_873:
	s_waitcnt vmcnt(4)
	v_lshlrev_b32_e32 v22, 16, v196
	v_and_b32_e32 v23, 0xffff0000, v196
	v_pk_add_f32 v[22:23], v[22:23], v[218:219] neg_lo:[0,1] neg_hi:[0,1]
	v_lshlrev_b32_e32 v24, 16, v197
	v_pk_mul_f32 v[22:23], v[22:23], v[220:221]
	v_and_b32_e32 v25, 0xffff0000, v197
	v_pk_fma_f32 v[22:23], v[66:67], v[22:23], v[70:71]
	s_and_b64 vcc, exec, s[36:37]
	v_pk_mul_f32 v[22:23], v[22:23], s[70:71] op_sel_hi:[1,0]
	s_nop 0
	v_pk_fma_f32 v[196:197], v[162:163], v[18:19], v[22:23]
	v_pk_add_f32 v[18:19], v[24:25], v[218:219] neg_lo:[0,1] neg_hi:[0,1]
	s_nop 0
	v_pk_mul_f32 v[18:19], v[18:19], v[220:221]
	s_nop 0
	v_pk_fma_f32 v[18:19], v[68:69], v[18:19], v[72:73]
	s_nop 0
	v_pk_mul_f32 v[18:19], v[18:19], s[70:71] op_sel_hi:[1,0]
	s_nop 0
	v_pk_fma_f32 v[198:199], v[162:163], v[20:21], v[18:19]
	s_cbranch_vccnz .LBB0_875
	v_cvt_pk_bf16_f32 v18, v196, v197
	v_cvt_pk_bf16_f32 v19, v198, v199
	global_store_dwordx2 v[204:205], v[18:19], off offset:288

.LBB0_877:
	s_or_b64 exec, exec, s[42:43]
	v_add_u32_e32 v19, 0xc0, v226
	ds_bpermute_b32 v18, v19, v172
	s_waitcnt lgkmcnt(0)
	ds_bpermute_b32 v20, v19, v189
	s_waitcnt vmcnt(3)
	v_lshlrev_b32_e32 v22, 16, v216
	v_and_b32_e32 v23, 0xffff0000, v216
	v_lshlrev_b32_e32 v24, 16, v217
	v_pk_add_f32 v[22:23], v[22:23], v[18:19] op_sel_hi:[1,0] neg_lo:[0,1] neg_hi:[0,1]
	v_and_b32_e32 v25, 0xffff0000, v217
	s_waitcnt lgkmcnt(0)
	v_pk_mul_f32 v[22:23], v[22:23], v[20:21] op_sel_hi:[1,0]
	s_and_b64 vcc, exec, s[36:37]
	v_pk_fma_f32 v[22:23], v[98:99], v[22:23], v[102:103]
	s_nop 0
	v_pk_mul_f32 v[22:23], v[22:23], s[70:71] op_sel_hi:[1,0]
	s_nop 0
	v_pk_fma_f32 v[98:99], v[162:163], v[14:15], v[22:23]
	v_pk_add_f32 v[14:15], v[24:25], v[18:19] op_sel_hi:[1,0] neg_lo:[0,1] neg_hi:[0,1]
	s_nop 0
	v_pk_mul_f32 v[14:15], v[14:15], v[20:21] op_sel_hi:[1,0]
	s_nop 0
	v_pk_fma_f32 v[14:15], v[100:101], v[14:15], v[104:105]
	s_nop 0
	v_pk_mul_f32 v[14:15], v[14:15], s[70:71] op_sel_hi:[1,0]
	s_nop 0
	v_pk_fma_f32 v[100:101], v[162:163], v[16:17], v[14:15]
	s_cbranch_vccnz .LBB0_879
	v_cvt_pk_bf16_f32 v14, v98, v99
	v_cvt_pk_bf16_f32 v15, v100, v101
	global_store_dwordx2 v[206:207], v[14:15], off
.LBB0_879:
	v_mov_b32_e32 v19, v18
	s_waitcnt vmcnt(2)
	v_lshlrev_b32_e32 v14, 16, v212
	v_and_b32_e32 v15, 0xffff0000, v212
	v_mov_b32_e32 v21, v20
	v_pk_add_f32 v[14:15], v[14:15], v[18:19] neg_lo:[0,1] neg_hi:[0,1]
	v_lshlrev_b32_e32 v16, 16, v213
	v_pk_mul_f32 v[14:15], v[14:15], v[20:21]
	v_and_b32_e32 v17, 0xffff0000, v213
	v_pk_fma_f32 v[14:15], v[86:87], v[14:15], v[90:91]
	s_and_b64 vcc, exec, s[36:37]
	v_pk_mul_f32 v[14:15], v[14:15], s[70:71] op_sel_hi:[1,0]
	s_nop 0
	v_pk_fma_f32 v[86:87], v[162:163], v[10:11], v[14:15]
	v_pk_add_f32 v[10:11], v[16:17], v[18:19] neg_lo:[0,1] neg_hi:[0,1]
	s_nop 0
	v_pk_mul_f32 v[10:11], v[10:11], v[20:21]
	s_nop 0
	v_pk_fma_f32 v[10:11], v[88:89], v[10:11], v[92:93]
	s_nop 0
	v_pk_mul_f32 v[10:11], v[10:11], s[70:71] op_sel_hi:[1,0]
	s_nop 0
	v_pk_fma_f32 v[88:89], v[162:163], v[12:13], v[10:11]
	s_cbranch_vccnz .LBB0_881
	v_cvt_pk_bf16_f32 v10, v86, v87
	v_cvt_pk_bf16_f32 v11, v88, v89
	global_store_dwordx2 v[206:207], v[10:11], off offset:32
.LBB0_881:
	s_waitcnt vmcnt(1)
	v_lshlrev_b32_e32 v10, 16, v210
	v_and_b32_e32 v11, 0xffff0000, v210
	v_pk_add_f32 v[10:11], v[10:11], v[18:19] neg_lo:[0,1] neg_hi:[0,1]
	v_lshlrev_b32_e32 v12, 16, v211
	v_pk_mul_f32 v[10:11], v[10:11], v[20:21]
	v_and_b32_e32 v13, 0xffff0000, v211
	v_pk_fma_f32 v[10:11], v[74:75], v[10:11], v[78:79]
	s_and_b64 vcc, exec, s[36:37]
	v_pk_mul_f32 v[10:11], v[10:11], s[70:71] op_sel_hi:[1,0]
	s_nop 0
	v_pk_fma_f32 v[74:75], v[162:163], v[6:7], v[10:11]
	v_pk_add_f32 v[6:7], v[12:13], v[18:19] neg_lo:[0,1] neg_hi:[0,1]
	s_nop 0
	v_pk_mul_f32 v[6:7], v[6:7], v[20:21]
	s_nop 0
	v_pk_fma_f32 v[6:7], v[76:77], v[6:7], v[80:81]
	s_nop 0
	v_pk_mul_f32 v[6:7], v[6:7], s[70:71] op_sel_hi:[1,0]
	s_nop 0
	v_pk_fma_f32 v[76:77], v[162:163], v[8:9], v[6:7]
	s_cbranch_vccnz .LBB0_883
	v_cvt_pk_bf16_f32 v6, v74, v75
	v_cvt_pk_bf16_f32 v7, v76, v77
	global_store_dwordx2 v[206:207], v[6:7], off offset:256
.LBB0_883:
	s_waitcnt vmcnt(0)
	v_lshlrev_b32_e32 v6, 16, v208
	v_and_b32_e32 v7, 0xffff0000, v208
	v_pk_add_f32 v[6:7], v[6:7], v[18:19] neg_lo:[0,1] neg_hi:[0,1]
	v_lshlrev_b32_e32 v8, 16, v209
	v_pk_mul_f32 v[6:7], v[6:7], v[20:21]
	v_and_b32_e32 v9, 0xffff0000, v209
	v_pk_fma_f32 v[6:7], v[66:67], v[6:7], v[70:71]
	s_and_b64 vcc, exec, s[36:37]
	v_pk_mul_f32 v[6:7], v[6:7], s[70:71] op_sel_hi:[1,0]
	s_nop 0
	v_pk_fma_f32 v[66:67], v[162:163], v[2:3], v[6:7]
	v_pk_add_f32 v[2:3], v[8:9], v[18:19] neg_lo:[0,1] neg_hi:[0,1]
	s_nop 0
	v_pk_mul_f32 v[2:3], v[2:3], v[20:21]
	s_nop 0
	v_pk_fma_f32 v[2:3], v[68:69], v[2:3], v[72:73]
	s_nop 0
	v_pk_mul_f32 v[2:3], v[2:3], s[70:71] op_sel_hi:[1,0]
	s_nop 0
	v_pk_fma_f32 v[68:69], v[162:163], v[4:5], v[2:3]
	s_cbranch_vccnz .LBB0_885
	v_cvt_pk_bf16_f32 v2, v66, v67
	v_cvt_pk_bf16_f32 v3, v68, v69
	global_store_dwordx2 v[206:207], v[2:3], off offset:288
